# P4 epilogue: rss row loads hoisted above the ALIGN barrier and conv-weight loads issued before the publish barrier; attention LDS-DMA issue moved to gaps a1-a4
# speedup vs baseline: 1.0301x; 1.0116x over previous
; __device__ __forceinline__ void attn_phase_fast(LAS unsigned char* lds, const bf16_t* q, const bf16_t* k, const bf16_t* vT, bf16_t* mixed, float lam, const int wave_s) {
;     ...
;                 ATT_DMA(nb, Kg + (size_t)(t + 1) * 64 * 512, Vg + (t + 1) * 64);
;             }
;             const LAS unsigned char* Qs = lds + 2 * ABUF + wid * (32 * QROW) + r32 * QROW + hi * 16;
;             int kxh = (kx >> 1) << 5, vxh = (vx >> 1) << 5, kq = cb + r32 * KROW + ((hi ^ (kx & 1)) << 4), vq = cb + KBUF + r32 * VROW + ((hi ^ (vx & 1)) << 4);
;             asm volatile("" : "+v"(kxh), "+v"(vxh), "+v"(kq), "+v"(vq));
;             const LAS unsigned char* Kb = lds + kq;
;             const LAS unsigned char* Vb = lds + vq;
; #pragma unroll
;             for (int m = 0; m < 2; ++m) {
;                 f32x16 s0, s1;
; #pragma unroll
;                 for (int i = 0; i < 16; ++i) { s0[i] = 0.f; s1[i] = 0.f; }
; #pragma unroll
;                 for (int d0 = 0; d0 < 4; ++d0) {
;                     const int kpos = ((m * 4 + d0) << 5) ^ kxh;
;                     const bf16x8 k0 = *(const LAS bf16x8*)(Kb + kpos), k1 = *(const LAS bf16x8*)(Kb + 32 * KROW + kpos);
;                     const bf16x8 qv = *(const LAS bf16x8*)(Qs + m * 128 + d0 * 32);
;                     s0 = MFMA32(k0, qv, s0); s1 = MFMA32(k1, qv, s1);
;                 }
;                 __builtin_amdgcn_sched_barrier(0);
;                 float ls = 0.f, ls2 = 0.f;
; #pragma unroll
;                 for (int i = 0; i < 16; ++i) { float e0 = __builtin_amdgcn_exp2f(s0[i]), e1 = __builtin_amdgcn_exp2f(s1[i]); asm volatile("" : "+v"(e0), "+v"(e1)); s0[i] = e0; s1[i] = e1; ls += e0; ls2 += e1; }
;                 ls += ls2;
;                 l[m] += ls;
;                 const bf16x8 p0 = packp(s0, 0), p1 = packp(s0, 1), p2 = packp(s1, 0), p3 = packp(s1, 1);
; #pragma unroll
;                 for (int db = 0; db < 4; ++db) {
;                     const LAS unsigned char* vb = Vb + db * 32 * VROW;
;                     const bf16x8 v0 = *(const LAS bf16x8*)(vb + (0 ^ vxh)), v1 = *(const LAS bf16x8*)(vb + (32 ^ vxh)), v2 = *(const LAS bf16x8*)(vb + (64 ^ vxh)), v3 = *(const LAS bf16x8*)(vb + (96 ^ vxh));
;                     o[m][db] = MFMA32(v0, p0, o[m][db]); o[m][db] = MFMA32(v1, p1, o[m][db]); o[m][db] = MFMA32(v2, p2, o[m][db]); o[m][db] = MFMA32(v3, p3, o[m][db]);
.Lattn_skip_tail:
	s_waitcnt lgkmcnt(7)
	v_mfma_f32_32x32x16_bf16 v[128:143], v[144:147], v[180:183], 0
	ds_read_b128 v[216:219], v228 offset:128
	s_add_i32 m0, s22, 0x8000
	s_nop 0
	global_load_lds_dwordx4 v208, s[6:7]
	s_waitcnt lgkmcnt(7)
	v_mfma_f32_32x32x16_bf16 v[128:143], v[148:151], v[184:187], v[128:143]
	ds_read_b128 v[220:223], v228 offset:160
	s_add_i32 m0, s24, 0x8000
	s_nop 0
	global_load_lds_dwordx4 v209, s[2:3]
	s_waitcnt lgkmcnt(7)
	v_mfma_f32_32x32x16_bf16 v[128:143], v[152:155], v[188:191], v[128:143]
	ds_read_b128 v[224:227], v228 offset:192
	s_add_i32 m0, s26, 0x8000
	s_nop 0
	global_load_lds_dwordx4 v210, s[6:7]
	s_waitcnt lgkmcnt(7)
	v_mfma_f32_32x32x16_bf16 v[128:143], v[156:159], v[192:195], v[128:143]
	ds_read_b128 v[234:237], v228 offset:224
	s_add_i32 m0, s27, 0x8000
	s_nop 0
	global_load_lds_dwordx4 v211, s[2:3]
	s_add_u32 s6, s6, 0x10000
	s_addc_u32 s7, s7, 0
	s_add_u32 s2, s2, 0x80
	s_addc_u32 s3, s3, 0
	s_waitcnt lgkmcnt(7)
	v_mfma_f32_32x32x16_bf16 v[144:159], v[164:167], v[180:183], 0
	ds_read_b128 v[180:183], v200
	ds_read_b128 v[238:241], v200 offset:8192
	v_exp_f32_e32 v128, v128
	v_exp_f32_e32 v129, v129
	v_add_f32_e32 v162, v162, v128
	v_exp_f32_e32 v130, v130
	s_waitcnt lgkmcnt(8)
	v_mfma_f32_32x32x16_bf16 v[144:159], v[168:171], v[184:187], v[144:159]
	ds_read_b128 v[184:187], v201
	ds_read_b128 v[242:245], v201 offset:8192
	v_add_f32_e32 v162, v162, v129
	v_exp_f32_e32 v131, v131
	v_add_f32_e32 v162, v162, v130
	v_cvt_pk_bf16_f32 v128, v128, v129
	s_waitcnt lgkmcnt(9)
	v_mfma_f32_32x32x16_bf16 v[144:159], v[172:175], v[188:191], v[144:159]
	ds_read_b128 v[188:191], v202
	ds_read_b128 v[246:249], v202 offset:8192
	v_exp_f32_e32 v132, v132
	v_add_f32_e32 v162, v162, v131
	v_exp_f32_e32 v133, v133
	v_add_f32_e32 v162, v162, v132
	s_waitcnt lgkmcnt(10)
	v_mfma_f32_32x32x16_bf16 v[144:159], v[212:215], v[192:195], v[144:159]
	ds_read_b128 v[192:195], v203
	ds_read_b128 v[212:215], v203 offset:8192
	v_cvt_pk_bf16_f32 v129, v130, v131
	v_exp_f32_e32 v134, v134
	v_add_f32_e32 v162, v162, v133
	v_exp_f32_e32 v135, v135
	s_waitcnt lgkmcnt(7)
	v_mfma_f32_32x32x16_bf16 v[164:179], v[180:183], v[216:219], 0
	ds_read_b128 v[250:253], v204
	v_add_f32_e32 v162, v162, v134
	v_cvt_pk_bf16_f32 v130, v132, v133
	v_exp_f32_e32 v136, v136
	v_add_f32_e32 v162, v162, v135
	s_waitcnt lgkmcnt(6)
	v_mfma_f32_32x32x16_bf16 v[164:179], v[184:187], v[220:223], v[164:179]
	v_exp_f32_e32 v137, v137
	v_add_f32_e32 v162, v162, v136
	v_cvt_pk_bf16_f32 v131, v134, v135
	v_exp_f32_e32 v138, v138
	s_waitcnt lgkmcnt(4)
	v_mfma_f32_32x32x16_bf16 v[164:179], v[188:191], v[224:227], v[164:179]
	v_add_f32_e32 v162, v162, v137
	v_exp_f32_e32 v139, v139
	v_add_f32_e32 v162, v162, v138
	v_cvt_pk_bf16_f32 v132, v136, v137
	s_waitcnt lgkmcnt(2)
	v_mfma_f32_32x32x16_bf16 v[164:179], v[192:195], v[234:237], v[164:179]
	v_exp_f32_e32 v140, v140
	v_add_f32_e32 v162, v162, v139
	v_exp_f32_e32 v141, v141
	v_add_f32_e32 v162, v162, v140
	v_mfma_f32_32x32x16_bf16 v[180:195], v[238:241], v[216:219], 0
	ds_read_b128 v[216:219], v204 offset:4096
	ds_read_b128 v[238:241], v204 offset:8192
	v_cvt_pk_bf16_f32 v133, v138, v139
	v_exp_f32_e32 v142, v142
	v_add_f32_e32 v162, v162, v141
	v_exp_f32_e32 v143, v143
	v_mfma_f32_32x32x16_bf16 v[180:195], v[242:245], v[220:223], v[180:195]
	ds_read_b128 v[220:223], v204 offset:12288
	ds_read_b128 v[242:245], v205
	v_add_f32_e32 v162, v162, v142
	v_cvt_pk_bf16_f32 v134, v140, v141
	v_add_f32_e32 v162, v162, v143
	v_cvt_pk_bf16_f32 v135, v142, v143
	v_mfma_f32_32x32x16_bf16 v[180:195], v[246:249], v[224:227], v[180:195]
	ds_read_b128 v[224:227], v205 offset:4096
	ds_read_b128 v[246:249], v205 offset:8192
	v_exp_f32_e32 v144, v144
	v_exp_f32_e32 v145, v145
	v_add_f32_e32 v162, v162, v144
	v_exp_f32_e32 v146, v146
	s_waitcnt lgkmcnt(7)
	v_mfma_f32_32x32x16_bf16 v[180:195], v[212:215], v[234:237], v[180:195]
	ds_read_b128 v[212:215], v205 offset:12288
	ds_read_b128 v[234:237], v206
	v_add_f32_e32 v162, v162, v145
	v_exp_f32_e32 v147, v147
	v_add_f32_e32 v162, v162, v146
	v_cvt_pk_bf16_f32 v136, v144, v145
	s_waitcnt lgkmcnt(8)
	v_mfma_f32_32x32x16_bf16 v[112:127], v[250:253], v[128:131], v[112:127]
	ds_read_b128 v[250:253], v206 offset:4096
	v_exp_f32_e32 v148, v148
	v_add_f32_e32 v162, v162, v147
	v_exp_f32_e32 v149, v149
	v_add_f32_e32 v162, v162, v148
	s_waitcnt lgkmcnt(8)
	v_mfma_f32_32x32x16_bf16 v[80:95], v[216:219], v[128:131], v[80:95]
	ds_read_b128 v[216:219], v206 offset:8192
	v_cvt_pk_bf16_f32 v137, v146, v147
	v_exp_f32_e32 v150, v150
	v_add_f32_e32 v162, v162, v149
	v_exp_f32_e32 v151, v151
	s_waitcnt lgkmcnt(8)
	v_mfma_f32_32x32x16_bf16 v[48:63], v[238:241], v[128:131], v[48:63]
	ds_read_b128 v[238:241], v206 offset:12288
	v_add_f32_e32 v162, v162, v150
	v_cvt_pk_bf16_f32 v138, v148, v149
	v_exp_f32_e32 v152, v152
	v_add_f32_e32 v162, v162, v151
	s_waitcnt lgkmcnt(8)
	v_mfma_f32_32x32x16_bf16 v[16:31], v[220:223], v[128:131], v[16:31]
	ds_read_b128 v[220:223], v207
	v_exp_f32_e32 v153, v153
	v_add_f32_e32 v162, v162, v152
	v_cvt_pk_bf16_f32 v139, v150, v151
	v_exp_f32_e32 v154, v154
	s_waitcnt lgkmcnt(8)
	v_mfma_f32_32x32x16_bf16 v[112:127], v[242:245], v[132:135], v[112:127]
	ds_read_b128 v[242:245], v207 offset:4096
	v_add_f32_e32 v162, v162, v153
	v_exp_f32_e32 v155, v155
	v_add_f32_e32 v162, v162, v154
	v_cvt_pk_bf16_f32 v140, v152, v153
	s_waitcnt lgkmcnt(8)
	v_mfma_f32_32x32x16_bf16 v[80:95], v[224:227], v[132:135], v[80:95]
	ds_read_b128 v[224:227], v207 offset:8192
	v_exp_f32_e32 v156, v156
	v_add_f32_e32 v162, v162, v155
	v_exp_f32_e32 v157, v157
	v_add_f32_e32 v162, v162, v156
	s_waitcnt lgkmcnt(8)
; #define LAS __attribute__((address_space(3)))
; #define MFMA32(a, b, c) __builtin_amdgcn_mfma_f32_32x32x16_bf16((a), (b), (c), 0, 0, 0)
; __device__ __forceinline__ void attn_phase_fast(LAS unsigned char* lds, const bf16_t* q, const bf16_t* k, const bf16_t* vT, bf16_t* mixed, float lam, const int wave_s) {
;     ...
;                 for (int i = 0; i < 16; ++i) { float e0 = __builtin_amdgcn_exp2f(s0[i]), e1 = __builtin_amdgcn_exp2f(s1[i]); asm volatile("" : "+v"(e0), "+v"(e1)); s0[i] = e0; s1[i] = e1; ls += e0; ls2 += e1; }
;                 ls += ls2;
;                 l[m] += ls;
;                 const bf16x8 p0 = packp(s0, 0), p1 = packp(s0, 1), p2 = packp(s1, 0), p3 = packp(s1, 1);
; #pragma unroll
;                 for (int db = 0; db < 4; ++db) {
;                     const LAS unsigned char* vb = Vb + db * 32 * VROW;
;                     const bf16x8 v0 = *(const LAS bf16x8*)(vb + (0 ^ vxh)), v1 = *(const LAS bf16x8*)(vb + (32 ^ vxh)), v2 = *(const LAS bf16x8*)(vb + (64 ^ vxh)), v3 = *(const LAS bf16x8*)(vb + (96 ^ vxh));
;                     o[m][db] = MFMA32(v0, p0, o[m][db]); o[m][db] = MFMA32(v1, p1, o[m][db]); o[m][db] = MFMA32(v2, p2, o[m][db]); o[m][db] = MFMA32(v3, p3, o[m][db]);
;                     if (db == 1) __builtin_amdgcn_sched_barrier(0);
;                 }
;                 __builtin_amdgcn_sched_barrier(0);
;             }
;             asm volatile("s_waitcnt vmcnt(0)" ::: "memory");
;             __syncthreads();
	v_mfma_f32_32x32x16_bf16 v[48:63], v[246:249], v[132:135], v[48:63]
	ds_read_b128 v[246:249], v207 offset:12288
	v_cvt_pk_bf16_f32 v141, v154, v155
	v_exp_f32_e32 v158, v158
	v_add_f32_e32 v162, v162, v157
	v_exp_f32_e32 v159, v159
	s_waitcnt lgkmcnt(8)
	v_mfma_f32_32x32x16_bf16 v[16:31], v[212:215], v[132:135], v[16:31]
	ds_read_b128 v[212:215], v204
	v_add_f32_e32 v162, v162, v158
	v_cvt_pk_bf16_f32 v142, v156, v157
	v_add_f32_e32 v162, v162, v159
	v_cvt_pk_bf16_f32 v143, v158, v159
	s_waitcnt lgkmcnt(8)
	v_mfma_f32_32x32x16_bf16 v[112:127], v[234:237], v[136:139], v[112:127]
	ds_read_b128 v[234:237], v204 offset:4096
	v_exp_f32_e32 v164, v164
	v_exp_f32_e32 v165, v165
	v_add_f32_e32 v163, v163, v164
	v_exp_f32_e32 v166, v166
	s_waitcnt lgkmcnt(8)
	v_mfma_f32_32x32x16_bf16 v[80:95], v[250:253], v[136:139], v[80:95]
	ds_read_b128 v[250:253], v204 offset:8192
	v_add_f32_e32 v163, v163, v165
	v_exp_f32_e32 v167, v167
	v_add_f32_e32 v163, v163, v166
	v_cvt_pk_bf16_f32 v164, v164, v165
	s_waitcnt lgkmcnt(8)
	v_mfma_f32_32x32x16_bf16 v[48:63], v[216:219], v[136:139], v[48:63]
	ds_read_b128 v[216:219], v204 offset:12288
	v_exp_f32_e32 v168, v168
	v_add_f32_e32 v163, v163, v167
	v_exp_f32_e32 v169, v169
	v_add_f32_e32 v163, v163, v168
	s_waitcnt lgkmcnt(8)
	v_mfma_f32_32x32x16_bf16 v[16:31], v[238:241], v[136:139], v[16:31]
	ds_read_b128 v[238:241], v205
	v_cvt_pk_bf16_f32 v165, v166, v167
	v_exp_f32_e32 v170, v170
	v_add_f32_e32 v163, v163, v169
	v_exp_f32_e32 v171, v171
	s_waitcnt lgkmcnt(8)
	v_mfma_f32_32x32x16_bf16 v[112:127], v[220:223], v[140:143], v[112:127]
	ds_read_b128 v[220:223], v205 offset:4096
	v_add_f32_e32 v163, v163, v170
	v_cvt_pk_bf16_f32 v166, v168, v169
	v_exp_f32_e32 v172, v172
	v_add_f32_e32 v163, v163, v171
	s_waitcnt lgkmcnt(8)
	v_mfma_f32_32x32x16_bf16 v[80:95], v[242:245], v[140:143], v[80:95]
	ds_read_b128 v[242:245], v205 offset:8192
	v_exp_f32_e32 v173, v173
	v_add_f32_e32 v163, v163, v172
	v_cvt_pk_bf16_f32 v167, v170, v171
	v_exp_f32_e32 v174, v174
	s_waitcnt lgkmcnt(8)
	v_mfma_f32_32x32x16_bf16 v[48:63], v[224:227], v[140:143], v[48:63]
	ds_read_b128 v[224:227], v205 offset:12288
	v_add_f32_e32 v163, v163, v173
	v_exp_f32_e32 v175, v175
	v_add_f32_e32 v163, v163, v174
	v_cvt_pk_bf16_f32 v168, v172, v173
	s_waitcnt lgkmcnt(8)
	v_mfma_f32_32x32x16_bf16 v[16:31], v[246:249], v[140:143], v[16:31]
	ds_read_b128 v[246:249], v206
	v_exp_f32_e32 v176, v176
	v_add_f32_e32 v163, v163, v175
	v_exp_f32_e32 v177, v177
	v_add_f32_e32 v163, v163, v176
	s_waitcnt lgkmcnt(8)
	v_mfma_f32_32x32x16_bf16 v[96:111], v[212:215], v[164:167], v[96:111]
	ds_read_b128 v[212:215], v206 offset:4096
	v_cvt_pk_bf16_f32 v169, v174, v175
	v_exp_f32_e32 v178, v178
	v_add_f32_e32 v163, v163, v177
	v_exp_f32_e32 v179, v179
	s_waitcnt lgkmcnt(8)
	v_mfma_f32_32x32x16_bf16 v[64:79], v[234:237], v[164:167], v[64:79]
	ds_read_b128 v[234:237], v206 offset:8192
	v_add_f32_e32 v163, v163, v178
	v_cvt_pk_bf16_f32 v170, v176, v177
	v_add_f32_e32 v163, v163, v179
	v_cvt_pk_bf16_f32 v171, v178, v179
	s_waitcnt lgkmcnt(8)
	v_mfma_f32_32x32x16_bf16 v[32:47], v[250:253], v[164:167], v[32:47]
	ds_read_b128 v[250:253], v206 offset:12288
	v_exp_f32_e32 v180, v180
	v_exp_f32_e32 v181, v181
	v_add_f32_e32 v163, v163, v180
	v_exp_f32_e32 v182, v182
	s_waitcnt lgkmcnt(8)
	v_mfma_f32_32x32x16_bf16 v[0:15], v[216:219], v[164:167], v[0:15]
	ds_read_b128 v[216:219], v207
	v_add_f32_e32 v163, v163, v181
	v_exp_f32_e32 v183, v183
	v_add_f32_e32 v163, v163, v182
	v_cvt_pk_bf16_f32 v172, v180, v181
	s_waitcnt lgkmcnt(8)
	v_mfma_f32_32x32x16_bf16 v[96:111], v[238:241], v[168:171], v[96:111]
	ds_read_b128 v[238:241], v207 offset:4096
	v_exp_f32_e32 v184, v184
	v_add_f32_e32 v163, v163, v183
	v_exp_f32_e32 v185, v185
	v_add_f32_e32 v163, v163, v184
	s_waitcnt lgkmcnt(8)
	v_mfma_f32_32x32x16_bf16 v[64:79], v[220:223], v[168:171], v[64:79]
	ds_read_b128 v[220:223], v207 offset:8192
	v_cvt_pk_bf16_f32 v173, v182, v183
	v_exp_f32_e32 v186, v186
	v_add_f32_e32 v163, v163, v185
	v_exp_f32_e32 v187, v187
	s_waitcnt lgkmcnt(8)
	v_mfma_f32_32x32x16_bf16 v[32:47], v[242:245], v[168:171], v[32:47]
	ds_read_b128 v[242:245], v207 offset:12288
	v_add_f32_e32 v163, v163, v186
	v_cvt_pk_bf16_f32 v174, v184, v185
	v_exp_f32_e32 v188, v188
	v_add_f32_e32 v163, v163, v187
	s_waitcnt lgkmcnt(8)
	v_mfma_f32_32x32x16_bf16 v[0:15], v[224:227], v[168:171], v[0:15]
	v_exp_f32_e32 v189, v189
	v_add_f32_e32 v163, v163, v188
	v_cvt_pk_bf16_f32 v175, v186, v187
	v_exp_f32_e32 v190, v190
	s_waitcnt lgkmcnt(7)
	v_mfma_f32_32x32x16_bf16 v[96:111], v[246:249], v[172:175], v[96:111]
	v_add_f32_e32 v163, v163, v189
	v_exp_f32_e32 v191, v191
	v_add_f32_e32 v163, v163, v190
	v_cvt_pk_bf16_f32 v176, v188, v189
	s_waitcnt lgkmcnt(6)
	v_mfma_f32_32x32x16_bf16 v[64:79], v[212:215], v[172:175], v[64:79]
	v_exp_f32_e32 v192, v192
	v_add_f32_e32 v163, v163, v191
	v_exp_f32_e32 v193, v193
	v_add_f32_e32 v163, v163, v192
	s_waitcnt lgkmcnt(5)
	v_mfma_f32_32x32x16_bf16 v[32:47], v[234:237], v[172:175], v[32:47]
	v_cvt_pk_bf16_f32 v177, v190, v191
	v_exp_f32_e32 v194, v194
	v_add_f32_e32 v163, v163, v193
	v_exp_f32_e32 v195, v195
	s_waitcnt lgkmcnt(4)
	v_mfma_f32_32x32x16_bf16 v[0:15], v[250:253], v[172:175], v[0:15]
	v_add_f32_e32 v163, v163, v194
	v_cvt_pk_bf16_f32 v178, v192, v193
	v_add_f32_e32 v163, v163, v195
	v_cvt_pk_bf16_f32 v179, v194, v195
	ds_read_b128 v[180:183], v228
	ds_read_b128 v[184:187], v228 offset:32
	ds_read_b128 v[188:191], v228 offset:64
	ds_read_b128 v[192:195], v228 offset:96
	s_waitcnt lgkmcnt(4)
	s_waitcnt vmcnt(0)
	s_barrier
; __device__ __forceinline__ void attn_phase_fast(LAS unsigned char* lds, const bf16_t* q, const bf16_t* k, const bf16_t* vT, bf16_t* mixed, float lam, const int wave_s) {
;     ...
;                 ATT_DMA(nb, Kg + (size_t)(t + 1) * 64 * 512, Vg + (t + 1) * 64);
;             }
;             const LAS unsigned char* Qs = lds + 2 * ABUF + wid * (32 * QROW) + r32 * QROW + hi * 16;
;             int kxh = (kx >> 1) << 5, vxh = (vx >> 1) << 5, kq = cb + r32 * KROW + ((hi ^ (kx & 1)) << 4), vq = cb + KBUF + r32 * VROW + ((hi ^ (vx & 1)) << 4);
;             asm volatile("" : "+v"(kxh), "+v"(vxh), "+v"(kq), "+v"(vq));
;             const LAS unsigned char* Kb = lds + kq;
;             const LAS unsigned char* Vb = lds + vq;
; #pragma unroll
;             for (int m = 0; m < 2; ++m) {
;                 f32x16 s0, s1;
; #pragma unroll
;                 for (int i = 0; i < 16; ++i) { s0[i] = 0.f; s1[i] = 0.f; }
; #pragma unroll
;                 for (int d0 = 0; d0 < 4; ++d0) {
;                     const int kpos = ((m * 4 + d0) << 5) ^ kxh;
;                     const bf16x8 k0 = *(const LAS bf16x8*)(Kb + kpos), k1 = *(const LAS bf16x8*)(Kb + 32 * KROW + kpos);
;                     const bf16x8 qv = *(const LAS bf16x8*)(Qs + m * 128 + d0 * 32);
;                     s0 = MFMA32(k0, qv, s0); s1 = MFMA32(k1, qv, s1);
;                 }
;                 __builtin_amdgcn_sched_barrier(0);
;                 float ls = 0.f, ls2 = 0.f;
; #pragma unroll
;                 for (int i = 0; i < 16; ++i) { float e0 = __builtin_amdgcn_exp2f(s0[i]), e1 = __builtin_amdgcn_exp2f(s1[i]); asm volatile("" : "+v"(e0), "+v"(e1)); s0[i] = e0; s1[i] = e1; ls += e0; ls2 += e1; }
;                 ls += ls2;
;                 l[m] += ls;
;                 const bf16x8 p0 = packp(s0, 0), p1 = packp(s0, 1), p2 = packp(s1, 0), p3 = packp(s1, 1);
; #pragma unroll
;                 for (int db = 0; db < 4; ++db) {
;                     const LAS unsigned char* vb = Vb + db * 32 * VROW;
;                     const bf16x8 v0 = *(const LAS bf16x8*)(vb + (0 ^ vxh)), v1 = *(const LAS bf16x8*)(vb + (32 ^ vxh)), v2 = *(const LAS bf16x8*)(vb + (64 ^ vxh)), v3 = *(const LAS bf16x8*)(vb + (96 ^ vxh));
;                     o[m][db] = MFMA32(v0, p0, o[m][db]); o[m][db] = MFMA32(v1, p1, o[m][db]); o[m][db] = MFMA32(v2, p2, o[m][db]); o[m][db] = MFMA32(v3, p3, o[m][db]);
	ds_read_b128 v[144:147], v196 offset:32768
	ds_read_b128 v[148:151], v197 offset:32768
	ds_read_b128 v[152:155], v198 offset:32768
	ds_read_b128 v[156:159], v199 offset:32768
	ds_read_b128 v[164:167], v196 offset:40960
	ds_read_b128 v[168:171], v197 offset:40960
	ds_read_b128 v[172:175], v198 offset:40960
	ds_read_b128 v[212:215], v199 offset:40960
	v_mfma_f32_32x32x16_bf16 v[96:111], v[216:219], v[176:179], v[96:111]
	v_mfma_f32_32x32x16_bf16 v[64:79], v[238:241], v[176:179], v[64:79]
	v_mfma_f32_32x32x16_bf16 v[32:47], v[220:223], v[176:179], v[32:47]
	v_mfma_f32_32x32x16_bf16 v[0:15], v[242:245], v[176:179], v[0:15]
	s_waitcnt lgkmcnt(7)
	v_mfma_f32_32x32x16_bf16 v[128:143], v[144:147], v[180:183], 0
	ds_read_b128 v[216:219], v228 offset:128
	s_mov_b32 m0, s22
	s_nop 0
	global_load_lds_dwordx4 v208, s[6:7]
	s_waitcnt lgkmcnt(7)
	v_mfma_f32_32x32x16_bf16 v[128:143], v[148:151], v[184:187], v[128:143]
	ds_read_b128 v[220:223], v228 offset:160
	s_mov_b32 m0, s24
	s_nop 0
	global_load_lds_dwordx4 v209, s[2:3]
	s_waitcnt lgkmcnt(7)
	v_mfma_f32_32x32x16_bf16 v[128:143], v[152:155], v[188:191], v[128:143]
	ds_read_b128 v[224:227], v228 offset:192
	s_mov_b32 m0, s26
	s_nop 0
	global_load_lds_dwordx4 v210, s[6:7]
	s_waitcnt lgkmcnt(7)
	v_mfma_f32_32x32x16_bf16 v[128:143], v[156:159], v[192:195], v[128:143]
	ds_read_b128 v[234:237], v228 offset:224
	s_mov_b32 m0, s27
	s_nop 0
	global_load_lds_dwordx4 v211, s[2:3]
	s_add_u32 s6, s6, 0x10000
	s_addc_u32 s7, s7, 0
	s_add_u32 s2, s2, 0x80
	s_addc_u32 s3, s3, 0
	s_waitcnt lgkmcnt(7)
	v_mfma_f32_32x32x16_bf16 v[144:159], v[164:167], v[180:183], 0
	ds_read_b128 v[180:183], v200 offset:32768
	ds_read_b128 v[238:241], v200 offset:40960
	v_exp_f32_e32 v128, v128
	v_exp_f32_e32 v129, v129
	v_add_f32_e32 v162, v162, v128
	v_exp_f32_e32 v130, v130
	s_waitcnt lgkmcnt(8)
	v_mfma_f32_32x32x16_bf16 v[144:159], v[168:171], v[184:187], v[144:159]
	ds_read_b128 v[184:187], v201 offset:32768
	ds_read_b128 v[242:245], v201 offset:40960
	v_add_f32_e32 v162, v162, v129
	v_exp_f32_e32 v131, v131
	v_add_f32_e32 v162, v162, v130
	v_cvt_pk_bf16_f32 v128, v128, v129
	s_waitcnt lgkmcnt(9)
	v_mfma_f32_32x32x16_bf16 v[144:159], v[172:175], v[188:191], v[144:159]
	ds_read_b128 v[188:191], v202 offset:32768
	ds_read_b128 v[246:249], v202 offset:40960
	v_exp_f32_e32 v132, v132
	v_add_f32_e32 v162, v162, v131
	v_exp_f32_e32 v133, v133
	v_add_f32_e32 v162, v162, v132
	s_waitcnt lgkmcnt(10)
	v_mfma_f32_32x32x16_bf16 v[144:159], v[212:215], v[192:195], v[144:159]
	ds_read_b128 v[192:195], v203 offset:32768
	ds_read_b128 v[212:215], v203 offset:40960
	v_cvt_pk_bf16_f32 v129, v130, v131
	v_exp_f32_e32 v134, v134
	v_add_f32_e32 v162, v162, v133
	v_exp_f32_e32 v135, v135
	s_waitcnt lgkmcnt(7)
	v_mfma_f32_32x32x16_bf16 v[164:179], v[180:183], v[216:219], 0
	ds_read_b128 v[250:253], v204 offset:32768
	v_add_f32_e32 v162, v162, v134
	v_cvt_pk_bf16_f32 v130, v132, v133
	v_exp_f32_e32 v136, v136
	v_add_f32_e32 v162, v162, v135
	s_waitcnt lgkmcnt(6)
	v_mfma_f32_32x32x16_bf16 v[164:179], v[184:187], v[220:223], v[164:179]
	v_exp_f32_e32 v137, v137
	v_add_f32_e32 v162, v162, v136
	v_cvt_pk_bf16_f32 v131, v134, v135
	v_exp_f32_e32 v138, v138
	s_waitcnt lgkmcnt(4)
	v_mfma_f32_32x32x16_bf16 v[164:179], v[188:191], v[224:227], v[164:179]
	v_add_f32_e32 v162, v162, v137
	v_exp_f32_e32 v139, v139
	v_add_f32_e32 v162, v162, v138
	v_cvt_pk_bf16_f32 v132, v136, v137
	s_waitcnt lgkmcnt(2)
	v_mfma_f32_32x32x16_bf16 v[164:179], v[192:195], v[234:237], v[164:179]
	v_exp_f32_e32 v140, v140
	v_add_f32_e32 v162, v162, v139
	v_exp_f32_e32 v141, v141
	v_add_f32_e32 v162, v162, v140
	v_mfma_f32_32x32x16_bf16 v[180:195], v[238:241], v[216:219], 0
	ds_read_b128 v[216:219], v204 offset:36864
	ds_read_b128 v[238:241], v204 offset:40960
	v_cvt_pk_bf16_f32 v133, v138, v139
	v_exp_f32_e32 v142, v142
	v_add_f32_e32 v162, v162, v141
	v_exp_f32_e32 v143, v143
	v_mfma_f32_32x32x16_bf16 v[180:195], v[242:245], v[220:223], v[180:195]
	ds_read_b128 v[220:223], v204 offset:45056
	ds_read_b128 v[242:245], v205 offset:32768
	v_add_f32_e32 v162, v162, v142
	v_cvt_pk_bf16_f32 v134, v140, v141
	v_add_f32_e32 v162, v162, v143
	v_cvt_pk_bf16_f32 v135, v142, v143
	v_mfma_f32_32x32x16_bf16 v[180:195], v[246:249], v[224:227], v[180:195]
	ds_read_b128 v[224:227], v205 offset:36864
	ds_read_b128 v[246:249], v205 offset:40960
	v_exp_f32_e32 v144, v144
	v_exp_f32_e32 v145, v145
	v_add_f32_e32 v162, v162, v144
	v_exp_f32_e32 v146, v146
	s_waitcnt lgkmcnt(7)
	v_mfma_f32_32x32x16_bf16 v[180:195], v[212:215], v[234:237], v[180:195]
	ds_read_b128 v[212:215], v205 offset:45056
	ds_read_b128 v[234:237], v206 offset:32768
	v_add_f32_e32 v162, v162, v145
	v_exp_f32_e32 v147, v147
	v_add_f32_e32 v162, v162, v146
	v_cvt_pk_bf16_f32 v136, v144, v145
	s_waitcnt lgkmcnt(8)
	v_mfma_f32_32x32x16_bf16 v[112:127], v[250:253], v[128:131], v[112:127]
	ds_read_b128 v[250:253], v206 offset:36864
	v_exp_f32_e32 v148, v148
	v_add_f32_e32 v162, v162, v147
	v_exp_f32_e32 v149, v149
	v_add_f32_e32 v162, v162, v148
	s_waitcnt lgkmcnt(8)
	v_mfma_f32_32x32x16_bf16 v[80:95], v[216:219], v[128:131], v[80:95]
	ds_read_b128 v[216:219], v206 offset:40960
	v_cvt_pk_bf16_f32 v137, v146, v147
	v_exp_f32_e32 v150, v150
	v_add_f32_e32 v162, v162, v149
	v_exp_f32_e32 v151, v151
	s_waitcnt lgkmcnt(8)
	v_mfma_f32_32x32x16_bf16 v[48:63], v[238:241], v[128:131], v[48:63]
	ds_read_b128 v[238:241], v206 offset:45056
	v_add_f32_e32 v162, v162, v150
	v_cvt_pk_bf16_f32 v138, v148, v149
	v_exp_f32_e32 v152, v152
	v_add_f32_e32 v162, v162, v151
	s_waitcnt lgkmcnt(8)
; #define LAS __attribute__((address_space(3)))
; #define MFMA32(a, b, c) __builtin_amdgcn_mfma_f32_32x32x16_bf16((a), (b), (c), 0, 0, 0)
; __device__ __forceinline__ void attn_phase_fast(LAS unsigned char* lds, const bf16_t* q, const bf16_t* k, const bf16_t* vT, bf16_t* mixed, float lam, const int wave_s) {
;     ...
;                 for (int i = 0; i < 16; ++i) { float e0 = __builtin_amdgcn_exp2f(s0[i]), e1 = __builtin_amdgcn_exp2f(s1[i]); asm volatile("" : "+v"(e0), "+v"(e1)); s0[i] = e0; s1[i] = e1; ls += e0; ls2 += e1; }
;                 ls += ls2;
;                 l[m] += ls;
;                 const bf16x8 p0 = packp(s0, 0), p1 = packp(s0, 1), p2 = packp(s1, 0), p3 = packp(s1, 1);
; #pragma unroll
;                 for (int db = 0; db < 4; ++db) {
;                     const LAS unsigned char* vb = Vb + db * 32 * VROW;
;                     const bf16x8 v0 = *(const LAS bf16x8*)(vb + (0 ^ vxh)), v1 = *(const LAS bf16x8*)(vb + (32 ^ vxh)), v2 = *(const LAS bf16x8*)(vb + (64 ^ vxh)), v3 = *(const LAS bf16x8*)(vb + (96 ^ vxh));
;                     o[m][db] = MFMA32(v0, p0, o[m][db]); o[m][db] = MFMA32(v1, p1, o[m][db]); o[m][db] = MFMA32(v2, p2, o[m][db]); o[m][db] = MFMA32(v3, p3, o[m][db]);
;                     if (db == 1) __builtin_amdgcn_sched_barrier(0);
;                 }
;                 __builtin_amdgcn_sched_barrier(0);
;             }
;             asm volatile("s_waitcnt vmcnt(0)" ::: "memory");
;             __syncthreads();
	v_mfma_f32_32x32x16_bf16 v[16:31], v[220:223], v[128:131], v[16:31]
	ds_read_b128 v[220:223], v207 offset:32768
	v_exp_f32_e32 v153, v153
	v_add_f32_e32 v162, v162, v152
	v_cvt_pk_bf16_f32 v139, v150, v151
	v_exp_f32_e32 v154, v154
	s_waitcnt lgkmcnt(8)
	v_mfma_f32_32x32x16_bf16 v[112:127], v[242:245], v[132:135], v[112:127]
	ds_read_b128 v[242:245], v207 offset:36864
	v_add_f32_e32 v162, v162, v153
	v_exp_f32_e32 v155, v155
	v_add_f32_e32 v162, v162, v154
	v_cvt_pk_bf16_f32 v140, v152, v153
	s_waitcnt lgkmcnt(8)
	v_mfma_f32_32x32x16_bf16 v[80:95], v[224:227], v[132:135], v[80:95]
	ds_read_b128 v[224:227], v207 offset:40960
	v_exp_f32_e32 v156, v156
	v_add_f32_e32 v162, v162, v155
	v_exp_f32_e32 v157, v157
	v_add_f32_e32 v162, v162, v156
	s_waitcnt lgkmcnt(8)
	v_mfma_f32_32x32x16_bf16 v[48:63], v[246:249], v[132:135], v[48:63]
	ds_read_b128 v[246:249], v207 offset:45056
	v_cvt_pk_bf16_f32 v141, v154, v155
	v_exp_f32_e32 v158, v158
	v_add_f32_e32 v162, v162, v157
	v_exp_f32_e32 v159, v159
	s_waitcnt lgkmcnt(8)
	v_mfma_f32_32x32x16_bf16 v[16:31], v[212:215], v[132:135], v[16:31]
	ds_read_b128 v[212:215], v204 offset:32768
	v_add_f32_e32 v162, v162, v158
	v_cvt_pk_bf16_f32 v142, v156, v157
	v_add_f32_e32 v162, v162, v159
	v_cvt_pk_bf16_f32 v143, v158, v159
	s_waitcnt lgkmcnt(8)
	v_mfma_f32_32x32x16_bf16 v[112:127], v[234:237], v[136:139], v[112:127]
	ds_read_b128 v[234:237], v204 offset:36864
	v_exp_f32_e32 v164, v164
	v_exp_f32_e32 v165, v165
	v_add_f32_e32 v163, v163, v164
	v_exp_f32_e32 v166, v166
	s_waitcnt lgkmcnt(8)
	v_mfma_f32_32x32x16_bf16 v[80:95], v[250:253], v[136:139], v[80:95]
	ds_read_b128 v[250:253], v204 offset:40960
	v_add_f32_e32 v163, v163, v165
	v_exp_f32_e32 v167, v167
	v_add_f32_e32 v163, v163, v166
	v_cvt_pk_bf16_f32 v164, v164, v165
	s_waitcnt lgkmcnt(8)
	v_mfma_f32_32x32x16_bf16 v[48:63], v[216:219], v[136:139], v[48:63]
	ds_read_b128 v[216:219], v204 offset:45056
	v_exp_f32_e32 v168, v168
	v_add_f32_e32 v163, v163, v167
	v_exp_f32_e32 v169, v169
	v_add_f32_e32 v163, v163, v168
	s_waitcnt lgkmcnt(8)
	v_mfma_f32_32x32x16_bf16 v[16:31], v[238:241], v[136:139], v[16:31]
	ds_read_b128 v[238:241], v205 offset:32768
	v_cvt_pk_bf16_f32 v165, v166, v167
	v_exp_f32_e32 v170, v170
	v_add_f32_e32 v163, v163, v169
	v_exp_f32_e32 v171, v171
	s_waitcnt lgkmcnt(8)
	v_mfma_f32_32x32x16_bf16 v[112:127], v[220:223], v[140:143], v[112:127]
	ds_read_b128 v[220:223], v205 offset:36864
	v_add_f32_e32 v163, v163, v170
	v_cvt_pk_bf16_f32 v166, v168, v169
	v_exp_f32_e32 v172, v172
	v_add_f32_e32 v163, v163, v171
	s_waitcnt lgkmcnt(8)
	v_mfma_f32_32x32x16_bf16 v[80:95], v[242:245], v[140:143], v[80:95]
	ds_read_b128 v[242:245], v205 offset:40960
	v_exp_f32_e32 v173, v173
	v_add_f32_e32 v163, v163, v172
	v_cvt_pk_bf16_f32 v167, v170, v171
	v_exp_f32_e32 v174, v174
	s_waitcnt lgkmcnt(8)
	v_mfma_f32_32x32x16_bf16 v[48:63], v[224:227], v[140:143], v[48:63]
	ds_read_b128 v[224:227], v205 offset:45056
	v_add_f32_e32 v163, v163, v173
	v_exp_f32_e32 v175, v175
	v_add_f32_e32 v163, v163, v174
	v_cvt_pk_bf16_f32 v168, v172, v173
	s_waitcnt lgkmcnt(8)
	v_mfma_f32_32x32x16_bf16 v[16:31], v[246:249], v[140:143], v[16:31]
	ds_read_b128 v[246:249], v206 offset:32768
	v_exp_f32_e32 v176, v176
	v_add_f32_e32 v163, v163, v175
	v_exp_f32_e32 v177, v177
	v_add_f32_e32 v163, v163, v176
	s_waitcnt lgkmcnt(8)
	v_mfma_f32_32x32x16_bf16 v[96:111], v[212:215], v[164:167], v[96:111]
	ds_read_b128 v[212:215], v206 offset:36864
	v_cvt_pk_bf16_f32 v169, v174, v175
	v_exp_f32_e32 v178, v178
	v_add_f32_e32 v163, v163, v177
	v_exp_f32_e32 v179, v179
	s_waitcnt lgkmcnt(8)
	v_mfma_f32_32x32x16_bf16 v[64:79], v[234:237], v[164:167], v[64:79]
	ds_read_b128 v[234:237], v206 offset:40960
	v_add_f32_e32 v163, v163, v178
	v_cvt_pk_bf16_f32 v170, v176, v177
	v_add_f32_e32 v163, v163, v179
	v_cvt_pk_bf16_f32 v171, v178, v179
	s_waitcnt lgkmcnt(8)
	v_mfma_f32_32x32x16_bf16 v[32:47], v[250:253], v[164:167], v[32:47]
	ds_read_b128 v[250:253], v206 offset:45056
	v_exp_f32_e32 v180, v180
	v_exp_f32_e32 v181, v181
	v_add_f32_e32 v163, v163, v180
	v_exp_f32_e32 v182, v182
	s_waitcnt lgkmcnt(8)
	v_mfma_f32_32x32x16_bf16 v[0:15], v[216:219], v[164:167], v[0:15]
	ds_read_b128 v[216:219], v207 offset:32768
	v_add_f32_e32 v163, v163, v181
	v_exp_f32_e32 v183, v183
	v_add_f32_e32 v163, v163, v182
	v_cvt_pk_bf16_f32 v172, v180, v181
	s_waitcnt lgkmcnt(8)
	v_mfma_f32_32x32x16_bf16 v[96:111], v[238:241], v[168:171], v[96:111]
	ds_read_b128 v[238:241], v207 offset:36864
	v_exp_f32_e32 v184, v184
	v_add_f32_e32 v163, v163, v183
	v_exp_f32_e32 v185, v185
	v_add_f32_e32 v163, v163, v184
	s_waitcnt lgkmcnt(8)
	v_mfma_f32_32x32x16_bf16 v[64:79], v[220:223], v[168:171], v[64:79]
	ds_read_b128 v[220:223], v207 offset:40960
	v_cvt_pk_bf16_f32 v173, v182, v183
	v_exp_f32_e32 v186, v186
	v_add_f32_e32 v163, v163, v185
	v_exp_f32_e32 v187, v187
	s_waitcnt lgkmcnt(8)
	v_mfma_f32_32x32x16_bf16 v[32:47], v[242:245], v[168:171], v[32:47]
	ds_read_b128 v[242:245], v207 offset:45056
	v_add_f32_e32 v163, v163, v186
	v_cvt_pk_bf16_f32 v174, v184, v185
	v_exp_f32_e32 v188, v188
	v_add_f32_e32 v163, v163, v187
	s_waitcnt lgkmcnt(8)
	v_mfma_f32_32x32x16_bf16 v[0:15], v[224:227], v[168:171], v[0:15]
	v_exp_f32_e32 v189, v189
	v_add_f32_e32 v163, v163, v188
	v_cvt_pk_bf16_f32 v175, v186, v187
	v_exp_f32_e32 v190, v190
	s_waitcnt lgkmcnt(7)
	v_mfma_f32_32x32x16_bf16 v[96:111], v[246:249], v[172:175], v[96:111]
	v_add_f32_e32 v163, v163, v189
	v_exp_f32_e32 v191, v191
	v_add_f32_e32 v163, v163, v190
	v_cvt_pk_bf16_f32 v176, v188, v189
	s_waitcnt lgkmcnt(6)
	v_mfma_f32_32x32x16_bf16 v[64:79], v[212:215], v[172:175], v[64:79]
	v_exp_f32_e32 v192, v192
	v_add_f32_e32 v163, v163, v191
	v_exp_f32_e32 v193, v193
	v_add_f32_e32 v163, v163, v192
	s_waitcnt lgkmcnt(5)
	v_mfma_f32_32x32x16_bf16 v[32:47], v[234:237], v[172:175], v[32:47]
	v_cvt_pk_bf16_f32 v177, v190, v191
	v_exp_f32_e32 v194, v194
	v_add_f32_e32 v163, v163, v193
	v_exp_f32_e32 v195, v195
	s_waitcnt lgkmcnt(4)
	v_mfma_f32_32x32x16_bf16 v[0:15], v[250:253], v[172:175], v[0:15]
	v_add_f32_e32 v163, v163, v194
	v_cvt_pk_bf16_f32 v178, v192, v193
	v_add_f32_e32 v163, v163, v195
	v_cvt_pk_bf16_f32 v179, v194, v195
	ds_read_b128 v[180:183], v228
	ds_read_b128 v[184:187], v228 offset:32
	ds_read_b128 v[188:191], v228 offset:64
	ds_read_b128 v[192:195], v228 offset:96
	s_waitcnt lgkmcnt(4)
	s_waitcnt vmcnt(0)
	s_add_i32 s44, s44, 2
	s_cmp_gt_u32 s44, s45
	s_barrier
; #define MFMA32(a, b, c) __builtin_amdgcn_mfma_f32_32x32x16_bf16((a), (b), (c), 0, 0, 0)
; __device__ __forceinline__ void attn_phase_fast(LAS unsigned char* lds, const bf16_t* q, const bf16_t* k, const bf16_t* vT, bf16_t* mixed, float lam, const int wave_s) {
;     ...
;                     o[m][db] = MFMA32(v0, p0, o[m][db]); o[m][db] = MFMA32(v1, p1, o[m][db]); o[m][db] = MFMA32(v2, p2, o[m][db]); o[m][db] = MFMA32(v3, p3, o[m][db]);
;                     if (db == 1) __builtin_amdgcn_sched_barrier(0);
;                 }
;                 __builtin_amdgcn_sched_barrier(0);
;             }
;             asm volatile("s_waitcnt vmcnt(0)" ::: "memory");
;             __syncthreads();
;         }
;         const float l0 = l[0] + __shfl_xor(l[0], 32), l1 = l[1] + __shfl_xor(l[1], 32);
;         const float c0 = 1.0f / l0, c1 = lam / l1;
;         float ss = 0.f;
; #pragma unroll
;         for (int db = 0; db < 4; ++db)
; #pragma unroll
;             for (int i = 0; i < 16; ++i) { const float v = o[0][db][i] * c0 - o[1][db][i] * c1; o[0][db][i] = v; ss += v * v; }
	s_cbranch_scc0 .Lattn_tile_loop
	v_mfma_f32_32x32x16_bf16 v[96:111], v[216:219], v[176:179], v[96:111]
	v_mfma_f32_32x32x16_bf16 v[64:79], v[238:241], v[176:179], v[64:79]
	v_mfma_f32_32x32x16_bf16 v[32:47], v[220:223], v[176:179], v[32:47]
	v_mfma_f32_32x32x16_bf16 v[0:15], v[242:245], v[176:179], v[0:15]
	s_mov_b32 m0, s50
	s_waitcnt lgkmcnt(0)
	v_and_b32_e32 v129, 64, v231
	v_xor_b32_e32 v128, 32, v231
	v_add_u32_e32 v129, 64, v129
	v_cmp_lt_i32_e32 vcc, v128, v129
	s_nop 1
	v_cndmask_b32_e32 v128, v231, v128, vcc
	v_lshlrev_b32_e32 v130, 2, v128
	v_mov_b32_e32 v128, v162
	v_mov_b32_e32 v129, v163
	ds_bpermute_b32 v132, v130, v128
	ds_bpermute_b32 v133, v130, v129
	s_lshl_b32 s0, s0, 1
	s_add_i32 s43, s43, s82
	s_cmpk_gt_i32 s43, 0x7ff
	s_waitcnt lgkmcnt(0)
	v_pk_add_f32 v[128:129], v[128:129], v[132:133]
	s_nop 0
	v_div_scale_f32 v131, s[2:3], v129, v129, v229
	v_rcp_f32_e32 v132, v131
	s_nop 0
	v_fma_f32 v133, -v131, v132, 1.0
	v_fmac_f32_e32 v132, v133, v132
	v_div_scale_f32 v133, vcc, v229, v129, v229
	v_mul_f32_e32 v134, v133, v132
	v_fma_f32 v135, -v131, v134, v133
	v_fmac_f32_e32 v134, v135, v132
	v_fma_f32 v131, -v131, v134, v133
	v_div_scale_f32 v133, s[2:3], v128, v128, 1.0
	v_rcp_f32_e32 v135, v133
	v_div_fmas_f32 v131, v131, v132, v134
	v_div_fixup_f32 v129, v131, v129, v229
	v_fma_f32 v131, -v133, v135, 1.0
	v_fmac_f32_e32 v135, v131, v135
	v_div_scale_f32 v131, vcc, 1.0, v128, 1.0
	v_mul_f32_e32 v132, v131, v135
	v_fma_f32 v134, -v133, v132, v131
	v_fmac_f32_e32 v132, v134, v135
	v_fma_f32 v131, -v133, v132, v131
	v_div_fmas_f32 v131, v131, v135, v132
	v_div_fixup_f32 v128, v131, v128, 1.0
	v_mov_b32_e32 v133, v96
	v_mov_b32_e32 v96, v113
	v_pk_mul_f32 v[96:97], v[96:97], v[128:129]
	v_mov_b32_e32 v132, v112
	v_sub_f32_e32 v113, v96, v97
	v_mov_b32_e32 v96, v114
	v_mov_b32_e32 v97, v98
	v_pk_mul_f32 v[96:97], v[96:97], v[128:129]
	v_mov_b32_e32 v98, v115
	v_sub_f32_e32 v114, v96, v97
	v_pk_mul_f32 v[96:97], v[98:99], v[128:129]
	v_pk_mul_f32 v[132:133], v[132:133], v[128:129]
	v_sub_f32_e32 v98, v96, v97
	v_mov_b32_e32 v96, v116
	v_mov_b32_e32 v97, v100
	v_pk_mul_f32 v[96:97], v[96:97], v[128:129]
	v_mov_b32_e32 v100, v117
	v_sub_f32_e32 v99, v96, v97
	v_pk_mul_f32 v[96:97], v[100:101], v[128:129]
	v_sub_f32_e32 v112, v132, v133
	v_sub_f32_e32 v100, v96, v97
	v_mov_b32_e32 v96, v118
	v_mov_b32_e32 v97, v102
	v_pk_mul_f32 v[96:97], v[96:97], v[128:129]
	v_mov_b32_e32 v102, v119
	v_sub_f32_e32 v101, v96, v97
	v_pk_mul_f32 v[96:97], v[102:103], v[128:129]
	s_nop 0
	v_sub_f32_e32 v102, v96, v97
	v_mov_b32_e32 v96, v120
	v_mov_b32_e32 v97, v104
	v_pk_mul_f32 v[96:97], v[96:97], v[128:129]
	v_mov_b32_e32 v104, v121
	v_sub_f32_e32 v103, v96, v97
	v_pk_mul_f32 v[96:97], v[104:105], v[128:129]
	s_nop 0
	v_sub_f32_e32 v104, v96, v97
	v_mov_b32_e32 v96, v122
	v_mov_b32_e32 v97, v106
	v_pk_mul_f32 v[96:97], v[96:97], v[128:129]
	v_mov_b32_e32 v106, v123
	v_sub_f32_e32 v105, v96, v97
	v_pk_mul_f32 v[96:97], v[106:107], v[128:129]
	s_nop 0
	v_sub_f32_e32 v106, v96, v97
	v_mov_b32_e32 v96, v124
	v_mov_b32_e32 v97, v108
	v_pk_mul_f32 v[96:97], v[96:97], v[128:129]
	v_mov_b32_e32 v108, v125
	v_sub_f32_e32 v107, v96, v97
	v_pk_mul_f32 v[96:97], v[108:109], v[128:129]
	s_nop 0
	v_sub_f32_e32 v108, v96, v97
	v_mov_b32_e32 v96, v126
	v_mov_b32_e32 v97, v110
	v_pk_mul_f32 v[96:97], v[96:97], v[128:129]
	v_mov_b32_e32 v110, v127
	v_sub_f32_e32 v109, v96, v97
	v_pk_mul_f32 v[96:97], v[110:111], v[128:129]
	s_nop 0
	v_sub_f32_e32 v110, v96, v97
	v_mov_b32_e32 v97, v64
	v_mov_b32_e32 v64, v81
	v_pk_mul_f32 v[64:65], v[64:65], v[128:129]
	v_mov_b32_e32 v96, v80
	v_sub_f32_e32 v81, v64, v65
	v_mov_b32_e32 v64, v82
	v_mov_b32_e32 v65, v66
	v_pk_mul_f32 v[64:65], v[64:65], v[128:129]
	v_mov_b32_e32 v66, v83
	v_sub_f32_e32 v82, v64, v65
	v_pk_mul_f32 v[64:65], v[66:67], v[128:129]
	v_pk_mul_f32 v[96:97], v[96:97], v[128:129]
	v_sub_f32_e32 v66, v64, v65
	v_mov_b32_e32 v64, v84
	v_mov_b32_e32 v65, v68
	v_pk_mul_f32 v[64:65], v[64:65], v[128:129]
	v_mov_b32_e32 v68, v85
	v_sub_f32_e32 v67, v64, v65
	v_pk_mul_f32 v[64:65], v[68:69], v[128:129]
	v_sub_f32_e32 v80, v96, v97
	v_sub_f32_e32 v68, v64, v65
	v_mov_b32_e32 v64, v86
	v_mov_b32_e32 v65, v70
	v_pk_mul_f32 v[64:65], v[64:65], v[128:129]
	v_mov_b32_e32 v70, v87
	v_sub_f32_e32 v69, v64, v65
	v_pk_mul_f32 v[64:65], v[70:71], v[128:129]
	s_nop 0
	v_sub_f32_e32 v70, v64, v65
	v_mov_b32_e32 v64, v88
	v_mov_b32_e32 v65, v72
	v_pk_mul_f32 v[64:65], v[64:65], v[128:129]
	v_mov_b32_e32 v72, v89
	v_sub_f32_e32 v71, v64, v65
	v_pk_mul_f32 v[64:65], v[72:73], v[128:129]
	s_nop 0
	v_sub_f32_e32 v72, v64, v65
	v_mov_b32_e32 v64, v90
	v_mov_b32_e32 v65, v74
	v_pk_mul_f32 v[64:65], v[64:65], v[128:129]
	v_mov_b32_e32 v74, v91
	v_sub_f32_e32 v73, v64, v65
	v_pk_mul_f32 v[64:65], v[74:75], v[128:129]
	s_nop 0
	v_sub_f32_e32 v74, v64, v65
	v_mov_b32_e32 v64, v92
	v_mov_b32_e32 v65, v76
	v_pk_mul_f32 v[64:65], v[64:65], v[128:129]
	v_mov_b32_e32 v76, v93
	v_sub_f32_e32 v75, v64, v65
	v_pk_mul_f32 v[64:65], v[76:77], v[128:129]
	s_nop 0
	v_sub_f32_e32 v76, v64, v65
	v_mov_b32_e32 v64, v94
	v_mov_b32_e32 v65, v78
	v_pk_mul_f32 v[64:65], v[64:65], v[128:129]
	v_mov_b32_e32 v78, v95
	v_sub_f32_e32 v77, v64, v65
	v_pk_mul_f32 v[64:65], v[78:79], v[128:129]
	s_nop 0
	v_sub_f32_e32 v78, v64, v65
	v_mov_b32_e32 v65, v32
	v_mov_b32_e32 v32, v49
	v_pk_mul_f32 v[32:33], v[32:33], v[128:129]
	v_mov_b32_e32 v64, v48
	v_sub_f32_e32 v49, v32, v33
	v_mov_b32_e32 v32, v50
	v_mov_b32_e32 v33, v34
	v_pk_mul_f32 v[32:33], v[32:33], v[128:129]
	v_mov_b32_e32 v34, v51
	v_sub_f32_e32 v50, v32, v33
	v_pk_mul_f32 v[32:33], v[34:35], v[128:129]
; __device__ __forceinline__ void attn_phase_fast(LAS unsigned char* lds, const bf16_t* q, const bf16_t* k, const bf16_t* vT, bf16_t* mixed, float lam, const int wave_s) {
;     ...
;         for (int db = 0; db < 4; ++db)
; #pragma unroll
;             for (int i = 0; i < 16; ++i) { const float v = o[0][db][i] * c0 - o[1][db][i] * c1; o[0][db][i] = v; ss += v * v; }
;         ss += __shfl_xor(ss, 32);
;         const float rstd = rsqrtf(ss * (1.0f / 128.0f) + EPSV);
	v_pk_mul_f32 v[64:65], v[64:65], v[128:129]
	v_sub_f32_e32 v34, v32, v33
	v_mov_b32_e32 v32, v52
	v_mov_b32_e32 v33, v36
	v_pk_mul_f32 v[32:33], v[32:33], v[128:129]
	v_mov_b32_e32 v36, v53
	v_sub_f32_e32 v35, v32, v33
	v_pk_mul_f32 v[32:33], v[36:37], v[128:129]
	v_sub_f32_e32 v48, v64, v65
	v_sub_f32_e32 v36, v32, v33
	v_mov_b32_e32 v32, v54
	v_mov_b32_e32 v33, v38
	v_pk_mul_f32 v[32:33], v[32:33], v[128:129]
	v_mov_b32_e32 v38, v55
	v_sub_f32_e32 v37, v32, v33
	v_pk_mul_f32 v[32:33], v[38:39], v[128:129]
	s_nop 0
	v_sub_f32_e32 v38, v32, v33
	v_mov_b32_e32 v32, v56
	v_mov_b32_e32 v33, v40
	v_pk_mul_f32 v[32:33], v[32:33], v[128:129]
	v_mov_b32_e32 v40, v57
	v_sub_f32_e32 v39, v32, v33
	v_pk_mul_f32 v[32:33], v[40:41], v[128:129]
	s_nop 0
	v_sub_f32_e32 v40, v32, v33
	v_mov_b32_e32 v32, v58
	v_mov_b32_e32 v33, v42
	v_pk_mul_f32 v[32:33], v[32:33], v[128:129]
	v_mov_b32_e32 v42, v59
	v_sub_f32_e32 v41, v32, v33
	v_pk_mul_f32 v[32:33], v[42:43], v[128:129]
	s_nop 0
	v_sub_f32_e32 v42, v32, v33
	v_mov_b32_e32 v32, v60
	v_mov_b32_e32 v33, v44
	v_pk_mul_f32 v[32:33], v[32:33], v[128:129]
	v_mov_b32_e32 v44, v61
	v_sub_f32_e32 v43, v32, v33
	v_pk_mul_f32 v[32:33], v[44:45], v[128:129]
	s_nop 0
	v_sub_f32_e32 v44, v32, v33
	v_mov_b32_e32 v32, v62
	v_mov_b32_e32 v33, v46
	v_pk_mul_f32 v[32:33], v[32:33], v[128:129]
	v_mov_b32_e32 v46, v63
	v_sub_f32_e32 v45, v32, v33
	v_pk_mul_f32 v[32:33], v[46:47], v[128:129]
	s_nop 0
	v_sub_f32_e32 v46, v32, v33
	v_mov_b32_e32 v32, v16
	v_mov_b32_e32 v33, v0
	v_mov_b32_e32 v0, v17
	v_pk_mul_f32 v[32:33], v[32:33], v[128:129]
	v_pk_mul_f32 v[0:1], v[0:1], v[128:129]
	v_sub_f32_e32 v32, v32, v33
	v_sub_f32_e32 v33, v0, v1
	v_mov_b32_e32 v0, v18
	v_mov_b32_e32 v1, v2
	v_pk_mul_f32 v[0:1], v[0:1], v[128:129]
	v_mov_b32_e32 v2, v19
	v_sub_f32_e32 v47, v0, v1
	v_pk_mul_f32 v[0:1], v[2:3], v[128:129]
	s_nop 0
	v_sub_f32_e32 v51, v0, v1
	v_mov_b32_e32 v0, v20
	v_mov_b32_e32 v1, v4
	v_pk_mul_f32 v[0:1], v[0:1], v[128:129]
	v_mov_b32_e32 v4, v21
	v_sub_f32_e32 v20, v0, v1
	v_pk_mul_f32 v[0:1], v[4:5], v[128:129]
	s_nop 0
	v_sub_f32_e32 v21, v0, v1
	v_mov_b32_e32 v0, v22
	v_mul_f32_e32 v22, v112, v112
	v_fmac_f32_e32 v22, v113, v113
	v_fmac_f32_e32 v22, v114, v114
	v_fmac_f32_e32 v22, v98, v98
	v_fmac_f32_e32 v22, v99, v99
	v_fmac_f32_e32 v22, v100, v100
	v_fmac_f32_e32 v22, v101, v101
	v_fmac_f32_e32 v22, v102, v102
	v_fmac_f32_e32 v22, v103, v103
	v_fmac_f32_e32 v22, v104, v104
	v_fmac_f32_e32 v22, v105, v105
	v_fmac_f32_e32 v22, v106, v106
	v_fmac_f32_e32 v22, v107, v107
	v_fmac_f32_e32 v22, v108, v108
	v_fmac_f32_e32 v22, v109, v109
	v_fmac_f32_e32 v22, v110, v110
	v_fmac_f32_e32 v22, v80, v80
	v_fmac_f32_e32 v22, v81, v81
	v_fmac_f32_e32 v22, v82, v82
	v_fmac_f32_e32 v22, v66, v66
	v_fmac_f32_e32 v22, v67, v67
	v_fmac_f32_e32 v22, v68, v68
	v_fmac_f32_e32 v22, v69, v69
	v_fmac_f32_e32 v22, v70, v70
	v_fmac_f32_e32 v22, v71, v71
	v_fmac_f32_e32 v22, v72, v72
	v_fmac_f32_e32 v22, v73, v73
	v_fmac_f32_e32 v22, v74, v74
	v_fmac_f32_e32 v22, v75, v75
	v_fmac_f32_e32 v22, v76, v76
	v_fmac_f32_e32 v22, v77, v77
	v_fmac_f32_e32 v22, v78, v78
	v_fmac_f32_e32 v22, v48, v48
	v_fmac_f32_e32 v22, v49, v49
	v_fmac_f32_e32 v22, v50, v50
	v_fmac_f32_e32 v22, v34, v34
	v_fmac_f32_e32 v22, v35, v35
	v_fmac_f32_e32 v22, v36, v36
	v_fmac_f32_e32 v22, v37, v37
	v_fmac_f32_e32 v22, v38, v38
	v_fmac_f32_e32 v22, v39, v39
	v_fmac_f32_e32 v22, v40, v40
	v_fmac_f32_e32 v22, v41, v41
	v_fmac_f32_e32 v22, v42, v42
	v_fmac_f32_e32 v22, v43, v43
	v_fmac_f32_e32 v22, v44, v44
	v_fmac_f32_e32 v22, v45, v45
	v_fmac_f32_e32 v22, v46, v46
	v_fmac_f32_e32 v22, v32, v32
	v_mov_b32_e32 v1, v6
	v_mov_b32_e32 v6, v23
	v_fmac_f32_e32 v22, v33, v33
	v_pk_mul_f32 v[0:1], v[0:1], v[128:129]
	v_pk_mul_f32 v[2:3], v[6:7], v[128:129]
	v_fmac_f32_e32 v22, v47, v47
	v_mov_b32_e32 v4, v2
	v_mov_b32_e32 v5, v0
	v_mov_b32_e32 v0, v3
	v_mov_b32_e32 v2, v24
	v_mov_b32_e32 v3, v8
	v_mov_b32_e32 v8, v25
	v_fmac_f32_e32 v22, v51, v51
	v_pk_add_f32 v[0:1], v[4:5], v[0:1] neg_lo:[0,1] neg_hi:[0,1]
	v_pk_mul_f32 v[2:3], v[2:3], v[128:129]
	v_pk_mul_f32 v[4:5], v[8:9], v[128:129]
	v_fmac_f32_e32 v22, v20, v20
	v_pk_mul_f32 v[16:17], v[0:1], v[0:1]
	v_mov_b32_e32 v6, v4
	v_mov_b32_e32 v7, v2
	v_mov_b32_e32 v2, v5
	v_mov_b32_e32 v4, v26
	v_mov_b32_e32 v5, v10
	v_mov_b32_e32 v10, v27
	v_fmac_f32_e32 v22, v21, v21
	v_pk_add_f32 v[2:3], v[6:7], v[2:3] neg_lo:[0,1] neg_hi:[0,1]
	v_pk_mul_f32 v[4:5], v[4:5], v[128:129]
	v_pk_mul_f32 v[6:7], v[10:11], v[128:129]
	v_add_f32_e32 v17, v17, v22
	v_pk_mul_f32 v[18:19], v[2:3], v[2:3]
	v_mov_b32_e32 v8, v6
	v_mov_b32_e32 v9, v4
	v_mov_b32_e32 v4, v7
	v_add_f32_e32 v16, v16, v17
	v_pk_add_f32 v[4:5], v[8:9], v[4:5] neg_lo:[0,1] neg_hi:[0,1]
	v_mov_b32_e32 v8, v129
	v_add_f32_e32 v16, v19, v16
	v_pk_mul_f32 v[10:11], v[4:5], v[4:5]
	v_pk_mul_f32 v[6:7], v[12:13], v[8:9] op_sel_hi:[1,0]
	v_add_f32_e32 v16, v18, v16
	v_pk_fma_f32 v[6:7], v[28:29], v[128:129], v[6:7] op_sel_hi:[1,0,1] neg_lo:[0,0,1] neg_hi:[0,0,1]
	v_add_f32_e32 v11, v11, v16
	v_pk_mul_f32 v[12:13], v[6:7], v[6:7]
	v_pk_mul_f32 v[8:9], v[14:15], v[8:9] op_sel_hi:[1,0]
	v_add_f32_e32 v10, v10, v11
	v_pk_fma_f32 v[8:9], v[30:31], v[128:129], v[8:9] op_sel_hi:[1,0,1] neg_lo:[0,0,1] neg_hi:[0,0,1]
	v_add_f32_e32 v10, v12, v10
	v_pk_mul_f32 v[14:15], v[8:9], v[8:9]
	v_add_f32_e32 v10, v13, v10
	v_add_f32_e32 v10, v14, v10
	v_add_f32_e32 v10, v15, v10
	ds_bpermute_b32 v11, v130, v10
	v_mbcnt_lo_u32_b32 v12, -1, 0
	v_mbcnt_hi_u32_b32 v12, -1, v12
	s_waitcnt lgkmcnt(0)
; __device__ __forceinline__ unsigned cvt_pk_bf16(float lo, float hi) { unsigned r; asm volatile("v_cvt_pk_bf16_f32 %0, %1, %2" : "=v"(r) : "v"(lo), "v"(hi)); return r; }
; __device__ __forceinline__ int lane_id() { int l; asm volatile("v_mbcnt_lo_u32_b32 %0, -1, 0\n\tv_mbcnt_hi_u32_b32 %0, -1, %0" : "=v"(l)); return l; }
; __device__ __forceinline__ void attn_phase_fast(LAS unsigned char* lds, const bf16_t* q, const bf16_t* k, const bf16_t* vT, bf16_t* mixed, float lam, const int wave_s) {
;     ...
;         ss += __shfl_xor(ss, 32);
;         const float rstd = rsqrtf(ss * (1.0f / 128.0f) + EPSV);
;         int lane2 = lane_id(); asm volatile("" : "+v"(lane2));
;         bf16_t* orow = mixed + ((size_t)tok0 + qb * 256 + wid * 32 + (lane2 & 31)) * DM + h * 128 + 4 * (lane2 >> 5);
; #pragma unroll
;         for (int db = 0; db < 4; ++db)
; #pragma unroll
;             for (int i4 = 0; i4 < 4; ++i4) {
;                 u32x2 w; w.x = cvt_pk_bf16(o[0][db][4 * i4] * rstd, o[0][db][4 * i4 + 1] * rstd); w.y = cvt_pk_bf16(o[0][db][4 * i4 + 2] * rstd, o[0][db][4 * i4 + 3] * rstd);
;                 *(u32x2*)(orow + 32 * db + 8 * i4) = w;
	v_add_f32_e32 v10, v10, v11
	v_fmamk_f32 v10, v10, 0x3c000000, v232
	v_mul_f32_e32 v11, 0x4b800000, v10
	v_cmp_gt_f32_e32 vcc, s42, v10
	s_nop 0
	v_and_b32_e32 v160, 31, v12
	v_cndmask_b32_e32 v10, v10, v11, vcc
	v_rsq_f32_e32 v10, v10
	v_ashrrev_i32_e32 v12, 3, v12
	v_and_b32_e32 v12, -4, v12
	v_ashrrev_i32_e32 v13, 31, v12
	v_mul_f32_e32 v11, 0x45800000, v10
	v_cndmask_b32_e32 v14, v10, v11, vcc
	v_lshl_add_u64 v[10:11], s[4:5], 0, v[160:161]
	v_lshlrev_b64 v[10:11], 11, v[10:11]
	v_lshl_add_u64 v[10:11], s[20:21], 0, v[10:11]
	v_lshl_add_u64 v[10:11], v[10:11], 0, s[0:1]
	v_lshl_add_u64 v[10:11], v[12:13], 1, v[10:11]
	v_mul_f32_e32 v12, v112, v14
	v_mul_f32_e32 v13, v113, v14
	v_cvt_pk_bf16_f32 v12, v12, v13
	v_mul_f32_e32 v13, v114, v14
	v_mul_f32_e32 v15, v98, v14
	v_cvt_pk_bf16_f32 v13, v13, v15
	global_store_dwordx2 v[10:11], v[12:13], off
	v_mul_f32_e32 v12, v99, v14
	v_mul_f32_e32 v13, v100, v14
	v_cvt_pk_bf16_f32 v12, v12, v13
	v_mul_f32_e32 v13, v101, v14
	v_mul_f32_e32 v15, v102, v14
	v_cvt_pk_bf16_f32 v13, v13, v15
	global_store_dwordx2 v[10:11], v[12:13], off offset:16
	v_mul_f32_e32 v12, v103, v14
	v_mul_f32_e32 v13, v104, v14
	v_cvt_pk_bf16_f32 v12, v12, v13
	v_mul_f32_e32 v13, v105, v14
	v_mul_f32_e32 v15, v106, v14
	v_cvt_pk_bf16_f32 v13, v13, v15
	global_store_dwordx2 v[10:11], v[12:13], off offset:32
	v_mul_f32_e32 v12, v107, v14
	v_mul_f32_e32 v13, v108, v14
	v_cvt_pk_bf16_f32 v12, v12, v13
	v_mul_f32_e32 v13, v109, v14
	v_mul_f32_e32 v15, v110, v14
	v_cvt_pk_bf16_f32 v13, v13, v15
	global_store_dwordx2 v[10:11], v[12:13], off offset:48
	v_mul_f32_e32 v12, v80, v14
	v_mul_f32_e32 v13, v81, v14
	v_cvt_pk_bf16_f32 v12, v12, v13
	v_mul_f32_e32 v13, v82, v14
	v_mul_f32_e32 v15, v66, v14
	v_cvt_pk_bf16_f32 v13, v13, v15
	global_store_dwordx2 v[10:11], v[12:13], off offset:64
	v_mul_f32_e32 v12, v67, v14
	v_mul_f32_e32 v13, v68, v14
	v_cvt_pk_bf16_f32 v12, v12, v13
	v_mul_f32_e32 v13, v69, v14
	v_mul_f32_e32 v15, v70, v14
	v_cvt_pk_bf16_f32 v13, v13, v15
	global_store_dwordx2 v[10:11], v[12:13], off offset:80
	v_mul_f32_e32 v12, v71, v14
	v_mul_f32_e32 v13, v72, v14
	v_cvt_pk_bf16_f32 v12, v12, v13
	v_mul_f32_e32 v13, v73, v14
	v_mul_f32_e32 v15, v74, v14
	v_cvt_pk_bf16_f32 v13, v13, v15
	global_store_dwordx2 v[10:11], v[12:13], off offset:96
	v_mul_f32_e32 v12, v75, v14
	v_mul_f32_e32 v13, v76, v14
	v_cvt_pk_bf16_f32 v12, v12, v13
	v_mul_f32_e32 v13, v77, v14
	v_mul_f32_e32 v15, v78, v14
	v_cvt_pk_bf16_f32 v13, v13, v15
	global_store_dwordx2 v[10:11], v[12:13], off offset:112
	v_mul_f32_e32 v12, v48, v14
	v_mul_f32_e32 v13, v49, v14
	v_cvt_pk_bf16_f32 v12, v12, v13
	v_mul_f32_e32 v13, v50, v14
	v_mul_f32_e32 v15, v34, v14
	v_cvt_pk_bf16_f32 v13, v13, v15
	global_store_dwordx2 v[10:11], v[12:13], off offset:128
	v_mul_f32_e32 v12, v35, v14
	v_mul_f32_e32 v13, v36, v14
	v_cvt_pk_bf16_f32 v12, v12, v13
	v_mul_f32_e32 v13, v37, v14
	v_mul_f32_e32 v15, v38, v14
	v_cvt_pk_bf16_f32 v13, v13, v15
	global_store_dwordx2 v[10:11], v[12:13], off offset:144
	v_mul_f32_e32 v12, v39, v14
	v_mul_f32_e32 v13, v40, v14
	v_cvt_pk_bf16_f32 v12, v12, v13
	v_mul_f32_e32 v13, v41, v14
	v_mul_f32_e32 v15, v42, v14
	v_cvt_pk_bf16_f32 v13, v13, v15
	global_store_dwordx2 v[10:11], v[12:13], off offset:160
	v_mul_f32_e32 v12, v43, v14
	v_mul_f32_e32 v13, v44, v14
	v_cvt_pk_bf16_f32 v12, v12, v13
	v_mul_f32_e32 v13, v45, v14
	v_mul_f32_e32 v15, v46, v14
	v_cvt_pk_bf16_f32 v13, v13, v15
	global_store_dwordx2 v[10:11], v[12:13], off offset:176
	v_mul_f32_e32 v12, v32, v14
	v_mul_f32_e32 v13, v33, v14
	v_cvt_pk_bf16_f32 v12, v12, v13
	v_mul_f32_e32 v13, v47, v14
	v_mul_f32_e32 v15, v51, v14
	v_cvt_pk_bf16_f32 v13, v13, v15
	global_store_dwordx2 v[10:11], v[12:13], off offset:192
	v_mul_f32_e32 v12, v20, v14
	v_mul_f32_e32 v13, v21, v14
	v_mul_f32_e32 v1, v1, v14
	v_mul_f32_e32 v0, v0, v14
	v_cvt_pk_bf16_f32 v12, v12, v13
	v_cvt_pk_bf16_f32 v13, v1, v0
	v_mul_f32_e32 v0, v3, v14
	v_mul_f32_e32 v1, v2, v14
	global_store_dwordx2 v[10:11], v[12:13], off offset:208
	v_cvt_pk_bf16_f32 v0, v0, v1
	v_mul_f32_e32 v1, v5, v14
	v_mul_f32_e32 v2, v4, v14
	v_cvt_pk_bf16_f32 v1, v1, v2
	global_store_dwordx2 v[10:11], v[0:1], off offset:224
	v_mul_f32_e32 v0, v6, v14
	v_mul_f32_e32 v1, v7, v14
	v_cvt_pk_bf16_f32 v0, v0, v1
	v_mul_f32_e32 v1, v8, v14
	v_mul_f32_e32 v2, v9, v14
	v_cvt_pk_bf16_f32 v1, v1, v2
	global_store_dwordx2 v[10:11], v[0:1], off offset:240
	s_cbranch_scc0 .LBB0_390

; #define PG8_STAGE(bufoff, gbase, voff) do { _Pragma("unroll") for (int _i = 0; _i < 2; ++_i) \
;         __builtin_amdgcn_global_load_lds((const unsigned*)((const char*)(gbase) + (voff)[_i]), (PG8_LAS unsigned*)(lds + (bufoff) + ldsw + _i * 8192), 16, 0, 0); } while (0)
; #define PG8_LDA(dst, b, h) do { _Pragma("unroll") for (int m = 0; m < 4; ++m) _Pragma("unroll") for (int k = 0; k < 2; ++k) dst[m][k] = *(const PG8_LAS bf16x8*)(lds + PG8_SA(b, h) + aoff + m * 2048 + k * 1024); } while (0)
; #define PG8_LDB(dst, b, h) do { _Pragma("unroll") for (int n = 0; n < 2; ++n) _Pragma("unroll") for (int k = 0; k < 2; ++k) dst[n][k] = *(const PG8_LAS bf16x8*)(lds + PG8_SB(b, h) + boff + n * 2048 + k * 1024); } while (0)
; #define PG8_MMA(ai, bj, At, Bt) do { __builtin_amdgcn_s_setprio(1); _Pragma("unroll") for (int m = 0; m < 4; ++m) _Pragma("unroll") for (int n = 0; n < 2; ++n) _Pragma("unroll") for (int k = 0; k < 2; ++k) \
;         acc[ai][bj][m][n] = __builtin_amdgcn_mfma_f32_16x16x32_bf16(Bt[n][k], At[m][k], acc[ai][bj][m][n], 0, 0, 0); __builtin_amdgcn_s_setprio(0); } while (0)
; #define PG8_BAR __builtin_amdgcn_s_barrier()
; template <class Epi, class Sched, bool ALIGN_EPI = false, bool SP2 = false>
; __device__ __forceinline__ void gemm_phase(PG8_LAS unsigned char* lds, const Gemm g, const Sched& S, const Epi& E, const int wave_s) {
;     ...
;             PG8_LDB(B0, 0, 0); PG8_LDB(B1, 0, 1); PG8_SCHED; PG8_LDA(At, 0, 0); PG8_STAGE(PG8_SA(1, 1), a1 + hstep, voffA);
;             PG8_WAIT_V(8); PG8_WAIT_L(0); PG8_BAR; PG8_MMA(0, 0, At, B0); PG8_MMA(0, 1, At, B1); PG8_BAR; PG8_SCHED;
;             PG8_LDA(At, 0, 1); PG8_STAGE(PG8_SB(0, 0), b2, voffB); PG8_STAGE(PG8_SB(0, 1), b2 + hstep, voffB); PG8_STAGE(PG8_SA(0, 0), a2, voffA);
;             PG8_WAIT_V(8); PG8_WAIT_L(0); PG8_BAR; PG8_MMA(1, 0, At, B0); PG8_MMA(1, 1, At, B1); PG8_BAR; PG8_SCHED;
;             PG8_LDB(B0, 1, 0); PG8_LDB(B1, 1, 1); PG8_SCHED; PG8_LDA(At, 1, 0); PG8_STAGE(PG8_SA(0, 1), a2 + hstep, voffA);
;             PG8_WAIT_V(8); PG8_WAIT_L(0); PG8_BAR; PG8_MMA(0, 0, At, B0); PG8_MMA(0, 1, At, B1); PG8_BAR; PG8_SCHED;
;             PG8_LDA(At, 1, 1); PG8_STAGE(PG8_SB(1, 0), b3, voffB); PG8_STAGE(PG8_SB(1, 1), b3 + hstep, voffB); PG8_STAGE(PG8_SA(1, 0), a3, voffA);
;             PG8_WAIT_V(8); PG8_WAIT_L(0); PG8_BAR; PG8_MMA(1, 0, At, B0); PG8_MMA(1, 1, At, B1); PG8_BAR; PG8_SCHED;
.LBB0_565:
	ds_read_b128 v[0:3], v239
	ds_read_b128 v[4:7], v239 offset:1024
	ds_read_b128 v[32:35], v239 offset:2048
	ds_read_b128 v[36:39], v239 offset:3072
	ds_read_b128 v[158:161], v240
	ds_read_b128 v[162:165], v240 offset:1024
	ds_read_b128 v[166:169], v240 offset:2048
	ds_read_b128 v[170:173], v240 offset:3072
	s_add_u32 s4, s0, 0xfffc0080
	s_addc_u32 s5, s1, -1
	s_cmp_eq_u32 s16, 12
	s_cselect_b32 s9, s95, s5
	s_cselect_b32 s8, s94, s4
	s_cselect_b32 s7, s11, s15
	s_cselect_b32 s6, s13, s14
	v_lshl_add_u64 v[206:207], s[0:1], 0, v[154:155]
	s_add_i32 m0, s2, 0xc000
	ds_read_b128 v[174:177], v241
	ds_read_b128 v[178:181], v241 offset:1024
	ds_read_b128 v[182:185], v241 offset:2048
	ds_read_b128 v[186:189], v241 offset:3072
	ds_read_b128 v[190:193], v241 offset:4096
	ds_read_b128 v[194:197], v241 offset:5120
	ds_read_b128 v[198:201], v241 offset:6144
	ds_read_b128 v[202:205], v241 offset:7168
	global_load_lds_dwordx4 v[206:207], off
	v_lshl_add_u64 v[206:207], s[0:1], 0, v[156:157]
	s_add_i32 m0, s2, 0xe000
	s_nop 0
	global_load_lds_dwordx4 v[206:207], off
	s_waitcnt vmcnt(8)
	s_waitcnt lgkmcnt(0)
	s_barrier
	s_setprio 1
	s_waitcnt lgkmcnt(0)
	v_mfma_f32_16x16x32_bf16 v[140:143], v[0:3], v[174:177], v[140:143]
	v_mfma_f32_16x16x32_bf16 v[136:139], v[32:35], v[174:177], v[136:139]
	v_mfma_f32_16x16x32_bf16 v[124:127], v[0:3], v[182:185], v[124:127]
	v_mfma_f32_16x16x32_bf16 v[120:123], v[32:35], v[182:185], v[120:123]
	v_mfma_f32_16x16x32_bf16 v[52:55], v[0:3], v[190:193], v[52:55]
	v_mfma_f32_16x16x32_bf16 v[48:51], v[32:35], v[190:193], v[48:51]
	v_mfma_f32_16x16x32_bf16 v[44:47], v[0:3], v[198:201], v[44:47]
	v_mfma_f32_16x16x32_bf16 v[40:43], v[32:35], v[198:201], v[40:43]
	v_mfma_f32_16x16x32_bf16 v[140:143], v[4:7], v[178:181], v[140:143]
	v_mfma_f32_16x16x32_bf16 v[136:139], v[36:39], v[178:181], v[136:139]
	v_mfma_f32_16x16x32_bf16 v[124:127], v[4:7], v[186:189], v[124:127]
	v_mfma_f32_16x16x32_bf16 v[120:123], v[36:39], v[186:189], v[120:123]
	v_mfma_f32_16x16x32_bf16 v[52:55], v[4:7], v[194:197], v[52:55]
	v_mfma_f32_16x16x32_bf16 v[48:51], v[36:39], v[194:197], v[48:51]
	v_mfma_f32_16x16x32_bf16 v[44:47], v[4:7], v[202:205], v[44:47]
	v_mfma_f32_16x16x32_bf16 v[40:43], v[36:39], v[202:205], v[40:43]
	s_setprio 0
	s_setprio 1
	v_mfma_f32_16x16x32_bf16 v[132:135], v[158:161], v[174:177], v[132:135]
	v_mfma_f32_16x16x32_bf16 v[128:131], v[166:169], v[174:177], v[128:131]
	v_mfma_f32_16x16x32_bf16 v[116:119], v[158:161], v[182:185], v[116:119]
	v_mfma_f32_16x16x32_bf16 v[112:115], v[166:169], v[182:185], v[112:115]
	v_mfma_f32_16x16x32_bf16 v[20:23], v[158:161], v[190:193], v[20:23]
	v_mfma_f32_16x16x32_bf16 v[16:19], v[166:169], v[190:193], v[16:19]
	v_mfma_f32_16x16x32_bf16 v[12:15], v[158:161], v[198:201], v[12:15]
	v_mfma_f32_16x16x32_bf16 v[8:11], v[166:169], v[198:201], v[8:11]
	v_mfma_f32_16x16x32_bf16 v[132:135], v[162:165], v[178:181], v[132:135]
	v_mfma_f32_16x16x32_bf16 v[128:131], v[170:173], v[178:181], v[128:131]
	v_mfma_f32_16x16x32_bf16 v[116:119], v[162:165], v[186:189], v[116:119]
	v_mfma_f32_16x16x32_bf16 v[112:115], v[170:173], v[186:189], v[112:115]
	v_mfma_f32_16x16x32_bf16 v[20:23], v[162:165], v[194:197], v[20:23]
	v_mfma_f32_16x16x32_bf16 v[16:19], v[170:173], v[194:197], v[16:19]
	v_mfma_f32_16x16x32_bf16 v[12:15], v[162:165], v[202:205], v[12:15]
	v_mfma_f32_16x16x32_bf16 v[8:11], v[170:173], v[202:205], v[8:11]
	s_setprio 0
	s_barrier
	s_add_i32 s4, s75, s33
	v_lshl_add_u64 v[206:207], s[6:7], 0, v[146:147]
	s_mov_b32 m0, s4
	ds_read_b128 v[174:177], v241 offset:16384
	ds_read_b128 v[178:181], v241 offset:17408
	ds_read_b128 v[182:185], v241 offset:18432
	ds_read_b128 v[186:189], v241 offset:19456
	ds_read_b128 v[190:193], v241 offset:20480
	ds_read_b128 v[194:197], v241 offset:21504
	ds_read_b128 v[198:201], v241 offset:22528
	ds_read_b128 v[202:205], v241 offset:23552
	global_load_lds_dwordx4 v[206:207], off
	s_add_i32 m0, s4, 0x2000
	s_add_u32 s18, s6, 0x40000
	v_lshl_add_u64 v[208:209], s[6:7], 0, v[150:151]
	s_addc_u32 s19, s7, 0
	s_add_i32 s4, s73, s33
	global_load_lds_dwordx4 v[208:209], off
	v_lshl_add_u64 v[210:211], s[18:19], 0, v[146:147]
	s_mov_b32 m0, s4
	v_lshl_add_u64 v[212:213], s[8:9], 0, v[148:149]
	global_load_lds_dwordx4 v[210:211], off
	v_lshl_add_u64 v[210:211], s[18:19], 0, v[150:151]
	s_add_i32 m0, s4, 0x2000
	s_nop 0
	global_load_lds_dwordx4 v[210:211], off
	v_lshl_add_u64 v[210:211], s[8:9], 0, v[144:145]
	s_mov_b32 m0, s2
	s_nop 0
	global_load_lds_dwordx4 v[210:211], off
	s_mov_b32 m0, s3
	s_nop 0
	global_load_lds_dwordx4 v[212:213], off
	s_waitcnt vmcnt(8)
	s_waitcnt lgkmcnt(0)
	s_barrier
; #define PG8_STAGE(bufoff, gbase, voff) do { _Pragma("unroll") for (int _i = 0; _i < 2; ++_i) \
;         __builtin_amdgcn_global_load_lds((const unsigned*)((const char*)(gbase) + (voff)[_i]), (PG8_LAS unsigned*)(lds + (bufoff) + ldsw + _i * 8192), 16, 0, 0); } while (0)
; #define PG8_LDA(dst, b, h) do { _Pragma("unroll") for (int m = 0; m < 4; ++m) _Pragma("unroll") for (int k = 0; k < 2; ++k) dst[m][k] = *(const PG8_LAS bf16x8*)(lds + PG8_SA(b, h) + aoff + m * 2048 + k * 1024); } while (0)
; #define PG8_LDB(dst, b, h) do { _Pragma("unroll") for (int n = 0; n < 2; ++n) _Pragma("unroll") for (int k = 0; k < 2; ++k) dst[n][k] = *(const PG8_LAS bf16x8*)(lds + PG8_SB(b, h) + boff + n * 2048 + k * 1024); } while (0)
; #define PG8_MMA(ai, bj, At, Bt) do { __builtin_amdgcn_s_setprio(1); _Pragma("unroll") for (int m = 0; m < 4; ++m) _Pragma("unroll") for (int n = 0; n < 2; ++n) _Pragma("unroll") for (int k = 0; k < 2; ++k) \
;         acc[ai][bj][m][n] = __builtin_amdgcn_mfma_f32_16x16x32_bf16(Bt[n][k], At[m][k], acc[ai][bj][m][n], 0, 0, 0); __builtin_amdgcn_s_setprio(0); } while (0)
; #define PG8_BAR __builtin_amdgcn_s_barrier()
; template <class Epi, class Sched, bool ALIGN_EPI = false, bool SP2 = false>
; __device__ __forceinline__ void gemm_phase(PG8_LAS unsigned char* lds, const Gemm g, const Sched& S, const Epi& E, const int wave_s) {
;     ...
;             PG8_LDB(B0, 0, 0); PG8_LDB(B1, 0, 1); PG8_SCHED; PG8_LDA(At, 0, 0); PG8_STAGE(PG8_SA(1, 1), a1 + hstep, voffA);
;             PG8_WAIT_V(8); PG8_WAIT_L(0); PG8_BAR; PG8_MMA(0, 0, At, B0); PG8_MMA(0, 1, At, B1); PG8_BAR; PG8_SCHED;
;             PG8_LDA(At, 0, 1); PG8_STAGE(PG8_SB(0, 0), b2, voffB); PG8_STAGE(PG8_SB(0, 1), b2 + hstep, voffB); PG8_STAGE(PG8_SA(0, 0), a2, voffA);
;             PG8_WAIT_V(8); PG8_WAIT_L(0); PG8_BAR; PG8_MMA(1, 0, At, B0); PG8_MMA(1, 1, At, B1); PG8_BAR; PG8_SCHED;
;             PG8_LDB(B0, 1, 0); PG8_LDB(B1, 1, 1); PG8_SCHED; PG8_LDA(At, 1, 0); PG8_STAGE(PG8_SA(0, 1), a2 + hstep, voffA);
;             PG8_WAIT_V(8); PG8_WAIT_L(0); PG8_BAR; PG8_MMA(0, 0, At, B0); PG8_MMA(0, 1, At, B1); PG8_BAR; PG8_SCHED;
;             PG8_LDA(At, 1, 1); PG8_STAGE(PG8_SB(1, 0), b3, voffB); PG8_STAGE(PG8_SB(1, 1), b3 + hstep, voffB); PG8_STAGE(PG8_SA(1, 0), a3, voffA);
;             PG8_WAIT_V(8); PG8_WAIT_L(0); PG8_BAR; PG8_MMA(1, 0, At, B0); PG8_MMA(1, 1, At, B1); PG8_BAR; PG8_SCHED;
	s_setprio 1
	s_waitcnt lgkmcnt(0)
	v_mfma_f32_16x16x32_bf16 v[108:111], v[0:3], v[174:177], v[108:111]
	v_mfma_f32_16x16x32_bf16 v[104:107], v[32:35], v[174:177], v[104:107]
	v_mfma_f32_16x16x32_bf16 v[92:95], v[0:3], v[182:185], v[92:95]
	v_mfma_f32_16x16x32_bf16 v[88:91], v[32:35], v[182:185], v[88:91]
	v_mfma_f32_16x16x32_bf16 v[60:63], v[0:3], v[190:193], v[60:63]
	v_mfma_f32_16x16x32_bf16 v[56:59], v[32:35], v[190:193], v[56:59]
	v_mfma_f32_16x16x32_bf16 v[0:3], v[0:3], v[198:201], v[76:79]
	v_mfma_f32_16x16x32_bf16 v[108:111], v[4:7], v[178:181], v[108:111]
	v_mfma_f32_16x16x32_bf16 v[104:107], v[36:39], v[178:181], v[104:107]
	v_mfma_f32_16x16x32_bf16 v[92:95], v[4:7], v[186:189], v[92:95]
	v_mfma_f32_16x16x32_bf16 v[88:91], v[36:39], v[186:189], v[88:91]
	v_mfma_f32_16x16x32_bf16 v[60:63], v[4:7], v[194:197], v[60:63]
	v_mfma_f32_16x16x32_bf16 v[56:59], v[36:39], v[194:197], v[56:59]
	v_mfma_f32_16x16x32_bf16 v[0:3], v[4:7], v[202:205], v[0:3]
	v_mfma_f32_16x16x32_bf16 v[4:7], v[32:35], v[198:201], v[72:75]
	v_mfma_f32_16x16x32_bf16 v[4:7], v[36:39], v[202:205], v[4:7]
	s_setprio 0
	s_setprio 1
	v_mfma_f32_16x16x32_bf16 v[72:75], v[158:161], v[182:185], v[84:87]
	v_mfma_f32_16x16x32_bf16 v[84:87], v[162:165], v[186:189], v[72:75]
	v_mfma_f32_16x16x32_bf16 v[72:75], v[166:169], v[182:185], v[80:83]
	v_mfma_f32_16x16x32_bf16 v[28:31], v[158:161], v[190:193], v[28:31]
	v_mfma_f32_16x16x32_bf16 v[24:27], v[166:169], v[190:193], v[24:27]
	v_mfma_f32_16x16x32_bf16 v[68:71], v[158:161], v[198:201], v[68:71]
	v_mfma_f32_16x16x32_bf16 v[64:67], v[166:169], v[198:201], v[64:67]
	v_mfma_f32_16x16x32_bf16 v[32:35], v[158:161], v[174:177], v[100:103]
	v_mfma_f32_16x16x32_bf16 v[36:39], v[166:169], v[174:177], v[96:99]
	v_mfma_f32_16x16x32_bf16 v[80:83], v[170:173], v[186:189], v[72:75]
	v_mfma_f32_16x16x32_bf16 v[28:31], v[162:165], v[194:197], v[28:31]
	v_mfma_f32_16x16x32_bf16 v[24:27], v[170:173], v[194:197], v[24:27]
	v_mfma_f32_16x16x32_bf16 v[68:71], v[162:165], v[202:205], v[68:71]
	v_mfma_f32_16x16x32_bf16 v[64:67], v[170:173], v[202:205], v[64:67]
	v_mfma_f32_16x16x32_bf16 v[32:35], v[162:165], v[178:181], v[32:35]
	v_mfma_f32_16x16x32_bf16 v[36:39], v[170:173], v[178:181], v[36:39]
	s_setprio 0
	s_barrier
	s_add_i32 s4, 0, 0x18000
	s_add_i32 s5, 0, 0x1c000
	v_add_u32_e32 v100, s4, v238
	v_add_u32_e32 v152, s5, v238
	ds_read_b128 v[72:75], v100
	ds_read_b128 v[76:79], v100 offset:1024
	ds_read_b128 v[96:99], v100 offset:2048
	ds_read_b128 v[100:103], v100 offset:3072
	ds_read_b128 v[158:161], v152
	ds_read_b128 v[162:165], v152 offset:1024
	ds_read_b128 v[166:169], v152 offset:2048
	ds_read_b128 v[170:173], v152 offset:3072
	s_add_u32 s8, s8, 0x40000
	s_addc_u32 s9, s9, 0
	s_mov_b32 m0, s76
	v_lshl_add_u64 v[214:215], s[8:9], 0, v[144:145]
	ds_read_b128 v[174:177], v241 offset:32768
	ds_read_b128 v[178:181], v241 offset:33792
	ds_read_b128 v[182:185], v241 offset:34816
	ds_read_b128 v[186:189], v241 offset:35840
	ds_read_b128 v[190:193], v241 offset:36864
	ds_read_b128 v[194:197], v241 offset:37888
	ds_read_b128 v[198:201], v241 offset:38912
	ds_read_b128 v[202:205], v241 offset:39936
	global_load_lds_dwordx4 v[214:215], off
	v_lshl_add_u64 v[214:215], s[8:9], 0, v[148:149]
	s_mov_b32 m0, s77
	s_nop 0
	global_load_lds_dwordx4 v[214:215], off
	s_waitcnt vmcnt(8)
	s_waitcnt lgkmcnt(0)
	s_barrier
	s_setprio 1
	s_waitcnt lgkmcnt(0)
	v_mfma_f32_16x16x32_bf16 v[140:143], v[72:75], v[174:177], v[140:143]
	v_mfma_f32_16x16x32_bf16 v[136:139], v[96:99], v[174:177], v[136:139]
	v_mfma_f32_16x16x32_bf16 v[124:127], v[72:75], v[182:185], v[124:127]
	v_mfma_f32_16x16x32_bf16 v[120:123], v[96:99], v[182:185], v[120:123]
	v_mfma_f32_16x16x32_bf16 v[52:55], v[72:75], v[190:193], v[52:55]
	v_mfma_f32_16x16x32_bf16 v[48:51], v[96:99], v[190:193], v[48:51]
	v_mfma_f32_16x16x32_bf16 v[44:47], v[72:75], v[198:201], v[44:47]
	v_mfma_f32_16x16x32_bf16 v[40:43], v[96:99], v[198:201], v[40:43]
	v_mfma_f32_16x16x32_bf16 v[140:143], v[76:79], v[178:181], v[140:143]
	v_mfma_f32_16x16x32_bf16 v[136:139], v[100:103], v[178:181], v[136:139]
	v_mfma_f32_16x16x32_bf16 v[124:127], v[76:79], v[186:189], v[124:127]
	v_mfma_f32_16x16x32_bf16 v[120:123], v[100:103], v[186:189], v[120:123]
	v_mfma_f32_16x16x32_bf16 v[52:55], v[76:79], v[194:197], v[52:55]
	v_mfma_f32_16x16x32_bf16 v[48:51], v[100:103], v[194:197], v[48:51]
	v_mfma_f32_16x16x32_bf16 v[44:47], v[76:79], v[202:205], v[44:47]
	v_mfma_f32_16x16x32_bf16 v[40:43], v[100:103], v[202:205], v[40:43]
	s_setprio 0
	s_setprio 1
	v_mfma_f32_16x16x32_bf16 v[132:135], v[158:161], v[174:177], v[132:135]
	v_mfma_f32_16x16x32_bf16 v[128:131], v[166:169], v[174:177], v[128:131]
	v_mfma_f32_16x16x32_bf16 v[116:119], v[158:161], v[182:185], v[116:119]
	v_mfma_f32_16x16x32_bf16 v[112:115], v[166:169], v[182:185], v[112:115]
	v_mfma_f32_16x16x32_bf16 v[20:23], v[158:161], v[190:193], v[20:23]
	v_mfma_f32_16x16x32_bf16 v[16:19], v[166:169], v[190:193], v[16:19]
	v_mfma_f32_16x16x32_bf16 v[12:15], v[158:161], v[198:201], v[12:15]
	v_mfma_f32_16x16x32_bf16 v[8:11], v[166:169], v[198:201], v[8:11]
	v_mfma_f32_16x16x32_bf16 v[132:135], v[162:165], v[178:181], v[132:135]
	v_mfma_f32_16x16x32_bf16 v[128:131], v[170:173], v[178:181], v[128:131]
	v_mfma_f32_16x16x32_bf16 v[116:119], v[162:165], v[186:189], v[116:119]
	v_mfma_f32_16x16x32_bf16 v[112:115], v[170:173], v[186:189], v[112:115]
	v_mfma_f32_16x16x32_bf16 v[20:23], v[162:165], v[194:197], v[20:23]
	v_mfma_f32_16x16x32_bf16 v[16:19], v[170:173], v[194:197], v[16:19]
	v_mfma_f32_16x16x32_bf16 v[12:15], v[162:165], v[202:205], v[12:15]
	v_mfma_f32_16x16x32_bf16 v[8:11], v[170:173], v[202:205], v[8:11]
	s_setprio 0
	s_barrier
; template <class Epi, class Sched, bool ALIGN_EPI = false, bool SP2 = false>
; __device__ __forceinline__ void gemm_phase(PG8_LAS unsigned char* lds, const Gemm g, const Sched& S, const Epi& E, const int wave_s) {
;     ...
;             PG8_WAIT_V(8); PG8_WAIT_L(0); PG8_BAR; PG8_MMA(0, 0, At, B0); PG8_MMA(0, 1, At, B1); PG8_BAR; PG8_SCHED;
;             PG8_LDA(At, 1, 1); PG8_STAGE(PG8_SB(1, 0), b3, voffB); PG8_STAGE(PG8_SB(1, 1), b3 + hstep, voffB); PG8_STAGE(PG8_SA(1, 0), a3, voffA);
;             PG8_WAIT_V(8); PG8_WAIT_L(0); PG8_BAR; PG8_MMA(1, 0, At, B0); PG8_MMA(1, 1, At, B1); PG8_BAR; PG8_SCHED;
;             } else {
;             PG8_LDB(B0, 0, 0); PG8_SCHED; PG8_LDA(At, 0, 0); PG8_STAGE(PG8_SA(1, 1), a1 + hstep, voffA);
;             PG8_WAIT_L(8); PG8_BAR; PG8_WAIT_L(0); PG8_MMA(0, 0, At, B0); PG8_BAR; PG8_SCHED;
;             PG8_LDB(B1, 0, 1); PG8_STAGE(PG8_SB(0, 0), b2, voffB);
;             PG8_BAR; PG8_WAIT_L(0); PG8_MMA(0, 1, At, B1); PG8_BAR;
;             PG8_LDA(At, 0, 1); PG8_STAGE(PG8_SA(0, 0), a2, voffA);
;             PG8_BAR; PG8_WAIT_L(0); PG8_MMA(1, 0, At, B0); PG8_BAR; PG8_SCHED;
;             PG8_STAGE(PG8_SB(0, 1), b2 + hstep, voffB);
;             PG8_WAIT_V(6); PG8_BAR; PG8_MMA(1, 1, At, B1); PG8_BAR;
;             PG8_LDB(B0, 1, 0); PG8_SCHED; PG8_LDA(At, 1, 0); PG8_STAGE(PG8_SA(0, 1), a2 + hstep, voffA);
;             PG8_WAIT_L(8); PG8_BAR; PG8_WAIT_L(0); PG8_MMA(0, 0, At, B0); PG8_BAR; PG8_SCHED;
;             PG8_LDB(B1, 1, 1); PG8_STAGE(PG8_SB(1, 0), b3, voffB);
;             PG8_BAR; PG8_WAIT_L(0); PG8_MMA(0, 1, At, B1); PG8_BAR;
;             PG8_LDA(At, 1, 1); PG8_STAGE(PG8_SA(1, 0), a3, voffA);
;             PG8_BAR; PG8_WAIT_L(0); PG8_MMA(1, 0, At, B0); PG8_BAR; PG8_SCHED;
;             PG8_STAGE(PG8_SB(1, 1), b3 + hstep, voffB);
;             PG8_WAIT_V(6); PG8_BAR; PG8_MMA(1, 1, At, B1); PG8_BAR;
;             }
;         }
;         if constexpr (ALIGN_EPI) { if (wr == 0) PG8_BAR; }
;     __device__ __forceinline__ void operator()(f32x4 (&acc)[2][2][4][2], const Unit& u, int wr, int wc, int fr, int fq) const {
;     ...
;                 const int tok = tok0 + ai * 128 + wr * 64 + m * 16 + fr;
;                 if (bnd) {
;                     const bool valid = (tok >= 0) && (tok < MTOK);
;                     float rs = 0.f; if (valid) rs = rsqrtf(rss[tok] * (1.0f / 1024.0f) + EPSV);
; #pragma unroll
	s_add_i32 s4, s4, s33
	v_lshl_add_u64 v[206:207], v[206:207], 0, s[64:65]
	s_mov_b32 m0, s4
	ds_read_b128 v[174:177], v241 offset:49152
	ds_read_b128 v[178:181], v241 offset:50176
	ds_read_b128 v[182:185], v241 offset:51200
	ds_read_b128 v[186:189], v241 offset:52224
	ds_read_b128 v[190:193], v241 offset:53248
	ds_read_b128 v[194:197], v241 offset:54272
	ds_read_b128 v[198:201], v241 offset:55296
	ds_read_b128 v[202:205], v241 offset:56320
	global_load_lds_dwordx4 v[206:207], off
	s_add_i32 m0, s4, 0x2000
	s_add_u32 s6, s6, 0x40080
	v_lshl_add_u64 v[206:207], v[208:209], 0, s[64:65]
	s_addc_u32 s7, s7, 0
	s_add_i32 s4, s5, s33
	global_load_lds_dwordx4 v[206:207], off
	v_lshl_add_u64 v[206:207], s[6:7], 0, v[146:147]
	s_mov_b32 m0, s4
	s_nop 0
	global_load_lds_dwordx4 v[206:207], off
	v_lshl_add_u64 v[206:207], s[6:7], 0, v[150:151]
	s_add_i32 m0, s4, 0x2000
	s_nop 0
	global_load_lds_dwordx4 v[206:207], off
	v_lshl_add_u64 v[206:207], v[210:211], 0, s[64:65]
	s_mov_b32 m0, s87
	s_nop 0
	global_load_lds_dwordx4 v[206:207], off
	v_lshl_add_u64 v[206:207], v[212:213], 0, s[64:65]
	s_mov_b32 m0, s72
	s_nop 0
	global_load_lds_dwordx4 v[206:207], off
	s_waitcnt vmcnt(8)
	s_waitcnt lgkmcnt(0)
	s_barrier
	s_setprio 1
	s_waitcnt lgkmcnt(0)
	v_mfma_f32_16x16x32_bf16 v[108:111], v[72:75], v[174:177], v[108:111]
	v_mfma_f32_16x16x32_bf16 v[92:95], v[72:75], v[182:185], v[92:95]
	v_mfma_f32_16x16x32_bf16 v[60:63], v[72:75], v[190:193], v[60:63]
	v_mfma_f32_16x16x32_bf16 v[0:3], v[72:75], v[198:201], v[0:3]
	v_mfma_f32_16x16x32_bf16 v[108:111], v[76:79], v[178:181], v[108:111]
	v_mfma_f32_16x16x32_bf16 v[104:107], v[96:99], v[174:177], v[104:107]
	v_mfma_f32_16x16x32_bf16 v[92:95], v[76:79], v[186:189], v[92:95]
	v_mfma_f32_16x16x32_bf16 v[88:91], v[96:99], v[182:185], v[88:91]
	v_mfma_f32_16x16x32_bf16 v[60:63], v[76:79], v[194:197], v[60:63]
	v_mfma_f32_16x16x32_bf16 v[56:59], v[96:99], v[190:193], v[56:59]
	v_mfma_f32_16x16x32_bf16 v[76:79], v[76:79], v[202:205], v[0:3]
	v_mfma_f32_16x16x32_bf16 v[0:3], v[96:99], v[198:201], v[4:7]
	v_mfma_f32_16x16x32_bf16 v[104:107], v[100:103], v[178:181], v[104:107]
	v_mfma_f32_16x16x32_bf16 v[88:91], v[100:103], v[186:189], v[88:91]
	v_mfma_f32_16x16x32_bf16 v[56:59], v[100:103], v[194:197], v[56:59]
	v_mfma_f32_16x16x32_bf16 v[72:75], v[100:103], v[202:205], v[0:3]
	s_setprio 0
	s_setprio 1
	v_mfma_f32_16x16x32_bf16 v[0:3], v[158:161], v[174:177], v[32:35]
	v_mfma_f32_16x16x32_bf16 v[100:103], v[162:165], v[178:181], v[0:3]
	v_mfma_f32_16x16x32_bf16 v[0:3], v[166:169], v[174:177], v[36:39]
	v_mfma_f32_16x16x32_bf16 v[96:99], v[170:173], v[178:181], v[0:3]
	v_mfma_f32_16x16x32_bf16 v[0:3], v[158:161], v[182:185], v[84:87]
	v_mfma_f32_16x16x32_bf16 v[84:87], v[162:165], v[186:189], v[0:3]
	v_mfma_f32_16x16x32_bf16 v[0:3], v[166:169], v[182:185], v[80:83]
	v_mfma_f32_16x16x32_bf16 v[80:83], v[170:173], v[186:189], v[0:3]
	v_mfma_f32_16x16x32_bf16 v[0:3], v[158:161], v[190:193], v[28:31]
	v_mfma_f32_16x16x32_bf16 v[28:31], v[162:165], v[194:197], v[0:3]
	v_mfma_f32_16x16x32_bf16 v[0:3], v[166:169], v[190:193], v[24:27]
	v_mfma_f32_16x16x32_bf16 v[24:27], v[170:173], v[194:197], v[0:3]
	v_mfma_f32_16x16x32_bf16 v[0:3], v[158:161], v[198:201], v[68:71]
	v_mfma_f32_16x16x32_bf16 v[68:71], v[162:165], v[202:205], v[0:3]
	v_mfma_f32_16x16x32_bf16 v[0:3], v[166:169], v[198:201], v[64:67]
	v_mfma_f32_16x16x32_bf16 v[64:67], v[170:173], v[202:205], v[0:3]
	s_setprio 0
	s_barrier
	s_add_i32 s16, s16, 2
	s_add_u32 s0, s0, 0x100
	s_addc_u32 s1, s1, 0
	s_add_u32 s14, s14, 0x100
	s_addc_u32 s15, s15, 0
	s_cmp_gt_u32 s16, 13
	s_cbranch_scc0 .LBB0_565
	s_mul_i32 s36, s12, 0xfe
	s_add_i32 s4, s36, -1
	v_add_u32_e32 v224, s48, v236
	v_add_u32_e32 v224, s4, v224
	v_ashrrev_i32_e32 v225, 31, v224
	v_lshl_add_u64 v[226:227], v[224:225], 2, s[60:61]
	global_load_dword v248, v[226:227], off
	global_load_dword v249, v[226:227], off offset:64
	global_load_dword v250, v[226:227], off offset:128
	global_load_dword v251, v[226:227], off offset:192
	global_load_dword v252, v[226:227], off offset:512
	global_load_dword v253, v[226:227], off offset:576
	global_load_dword v229, v[226:227], off offset:640
	global_load_dword v230, v[226:227], off offset:704
	s_and_b64 vcc, exec, s[80:81]
	s_cbranch_vccz .LBB0_568
	s_barrier
.LBB0_568:
	s_mul_i32 s36, s12, 0xfe
	s_add_i32 s4, s36, -1
	s_and_b32 s0, s4, 0xf00
	s_cmpk_lg_i32 s0, 0xf00
	s_cselect_b64 s[0:1], -1, 0
	s_add_i32 s5, s12, 0xfffffdfc
	s_cmp_gt_u32 s5, 0xfffffdfc
	v_mov_b32_e32 v190, v237
	v_mov_b32_e32 v228, v236
	s_cselect_b64 s[6:7], -1, 0
	s_and_b64 s[12:13], s[6:7], s[0:1]
	v_add_u32_e32 v245, s48, v228
	v_add_u32_e32 v152, s4, v245
	s_mov_b64 s[0:1], -1
	s_and_b64 vcc, exec, s[12:13]
	s_mov_b32 s93, s17
	s_cbranch_vccz .LBB0_570
	v_ashrrev_i32_e32 v1, 31, v152
	v_mov_b32_e32 v0, v152
	v_lshl_add_u64 v[0:1], v[0:1], 2, s[60:61]
	s_mov_b32 s0, 0x800000
	s_waitcnt vmcnt(0)
	v_mov_b32_e32 v0, v248
	v_fmamk_f32 v0, v0, 0x3a800000, v242
	v_mul_f32_e32 v1, 0x4b800000, v0
	v_cmp_gt_f32_e32 vcc, s0, v0
	s_mov_b64 s[0:1], 0
	s_nop 0
	v_cndmask_b32_e32 v0, v0, v1, vcc
	v_rsq_f32_e32 v0, v0
	s_nop 0
	v_mul_f32_e32 v1, 0x45800000, v0
	v_cndmask_b32_e32 v4, v0, v1, vcc
	v_pk_mul_f32 v[34:35], v[142:143], v[4:5] op_sel_hi:[1,0]
	v_pk_mul_f32 v[32:33], v[140:141], v[4:5] op_sel_hi:[1,0]
	v_pk_mul_f32 v[2:3], v[138:139], v[4:5] op_sel_hi:[1,0]
	v_pk_mul_f32 v[0:1], v[136:137], v[4:5] op_sel_hi:[1,0]
	v_pk_mul_f32 v[38:39], v[134:135], v[4:5] op_sel_hi:[1,0]
	v_pk_mul_f32 v[36:37], v[132:133], v[4:5] op_sel_hi:[1,0]
	v_pk_mul_f32 v[6:7], v[130:131], v[4:5] op_sel_hi:[1,0]
	v_pk_mul_f32 v[4:5], v[128:129], v[4:5] op_sel_hi:[1,0]

;     __device__ __forceinline__ void operator()(f32x4 (&acc)[2][2][4][2], const Unit& u, int wr, int wc, int fr, int fq) const {
;     ...
;                     const float rs = rsqrtf(rss[tok] * (1.0f / 1024.0f) + EPSV);
; #pragma unroll
;                     for (int bj = 0; bj < 2; ++bj)
; #pragma unroll
;                         for (int n = 0; n < 2; ++n) acc[ai][bj][m][n] = acc[ai][bj][m][n] * rs;
.LBB0_574:
	v_cndmask_b32_e64 v129, 0, 1, s[12:13]
	v_add_u32_e32 v128, 16, v152
	v_cmp_ne_u32_e64 s[6:7], 1, v129
	s_andn2_b64 vcc, exec, s[12:13]
	s_mov_b64 s[0:1], -1
	s_cbranch_vccnz .LBB0_588
	v_ashrrev_i32_e32 v129, 31, v128
	v_lshl_add_u64 v[130:131], v[128:129], 2, s[60:61]
	s_mov_b32 s0, 0x800000
	s_waitcnt vmcnt(0)
	v_mov_b32_e32 v129, v249
	v_fmamk_f32 v129, v129, 0x3a800000, v242
	v_mul_f32_e32 v130, 0x4b800000, v129
	v_cmp_gt_f32_e32 vcc, s0, v129
	s_nop 1
	v_cndmask_b32_e32 v129, v129, v130, vcc
	v_rsq_f32_e32 v129, v129
	s_nop 0
	v_mul_f32_e32 v130, 0x45800000, v129
	v_cndmask_b32_e32 v130, v129, v130, vcc
	v_pk_mul_f32 v[192:193], v[126:127], v[130:131] op_sel_hi:[1,0]
	v_pk_mul_f32 v[194:195], v[124:125], v[130:131] op_sel_hi:[1,0]
	v_pk_mul_f32 v[158:159], v[122:123], v[130:131] op_sel_hi:[1,0]
	v_pk_mul_f32 v[160:161], v[120:121], v[130:131] op_sel_hi:[1,0]
	v_pk_mul_f32 v[196:197], v[118:119], v[130:131] op_sel_hi:[1,0]
	v_pk_mul_f32 v[198:199], v[116:117], v[130:131] op_sel_hi:[1,0]
	v_pk_mul_f32 v[162:163], v[114:115], v[130:131] op_sel_hi:[1,0]
	v_pk_mul_f32 v[164:165], v[112:113], v[130:131] op_sel_hi:[1,0]
	s_cbranch_execz .LBB0_589

;     __device__ __forceinline__ void operator()(f32x4 (&acc)[2][2][4][2], const Unit& u, int wr, int wc, int fr, int fq) const {
;     ...
;                     const float rs = rsqrtf(rss[tok] * (1.0f / 1024.0f) + EPSV);
; #pragma unroll
;                     for (int bj = 0; bj < 2; ++bj)
; #pragma unroll
;                         for (int n = 0; n < 2; ++n) acc[ai][bj][m][n] = acc[ai][bj][m][n] * rs;
.LBB0_577:
	v_ashrrev_i32_e32 v113, 31, v112
	v_lshl_add_u64 v[114:115], v[112:113], 2, s[60:61]
	s_mov_b32 s0, 0x800000
	s_waitcnt vmcnt(0)
	v_mov_b32_e32 v113, v250
	v_fmamk_f32 v113, v113, 0x3a800000, v242
	v_mul_f32_e32 v114, 0x4b800000, v113
	v_cmp_gt_f32_e32 vcc, s0, v113
	s_nop 1
	v_cndmask_b32_e32 v113, v113, v114, vcc
	v_rsq_f32_e32 v113, v113
	s_nop 0
	v_mul_f32_e32 v114, 0x45800000, v113
	v_cndmask_b32_e32 v114, v113, v114, vcc
	v_pk_mul_f32 v[200:201], v[54:55], v[114:115] op_sel_hi:[1,0]
	v_pk_mul_f32 v[202:203], v[52:53], v[114:115] op_sel_hi:[1,0]
	v_pk_mul_f32 v[166:167], v[50:51], v[114:115] op_sel_hi:[1,0]
	v_pk_mul_f32 v[168:169], v[48:49], v[114:115] op_sel_hi:[1,0]
	v_pk_mul_f32 v[204:205], v[22:23], v[114:115] op_sel_hi:[1,0]
	v_pk_mul_f32 v[206:207], v[20:21], v[114:115] op_sel_hi:[1,0]
	v_pk_mul_f32 v[170:171], v[18:19], v[114:115] op_sel_hi:[1,0]
	v_pk_mul_f32 v[172:173], v[16:17], v[114:115] op_sel_hi:[1,0]
	s_cbranch_execz .LBB0_593

;     __device__ __forceinline__ void operator()(f32x4 (&acc)[2][2][4][2], const Unit& u, int wr, int wc, int fr, int fq) const {
;     ...
;                     const float rs = rsqrtf(rss[tok] * (1.0f / 1024.0f) + EPSV);
; #pragma unroll
;                     for (int bj = 0; bj < 2; ++bj)
; #pragma unroll
;                         for (int n = 0; n < 2; ++n) acc[ai][bj][m][n] = acc[ai][bj][m][n] * rs;
.LBB0_579:
	v_ashrrev_i32_e32 v113, 31, v112
	v_lshl_add_u64 v[16:17], v[112:113], 2, s[60:61]
	s_mov_b32 s0, 0x800000
	s_waitcnt vmcnt(0)
	v_mov_b32_e32 v16, v251
	v_fmamk_f32 v16, v16, 0x3a800000, v242
	v_mul_f32_e32 v17, 0x4b800000, v16
	v_cmp_gt_f32_e32 vcc, s0, v16
	s_nop 1
	v_cndmask_b32_e32 v16, v16, v17, vcc
	v_rsq_f32_e32 v16, v16
	s_nop 0
	v_mul_f32_e32 v17, 0x45800000, v16
	v_cndmask_b32_e32 v20, v16, v17, vcc
	v_pk_mul_f32 v[50:51], v[46:47], v[20:21] op_sel_hi:[1,0]
	v_pk_mul_f32 v[48:49], v[44:45], v[20:21] op_sel_hi:[1,0]
	v_pk_mul_f32 v[18:19], v[42:43], v[20:21] op_sel_hi:[1,0]
	v_pk_mul_f32 v[16:17], v[40:41], v[20:21] op_sel_hi:[1,0]
	v_pk_mul_f32 v[54:55], v[14:15], v[20:21] op_sel_hi:[1,0]
	v_pk_mul_f32 v[52:53], v[12:13], v[20:21] op_sel_hi:[1,0]
	v_pk_mul_f32 v[22:23], v[10:11], v[20:21] op_sel_hi:[1,0]
	v_pk_mul_f32 v[20:21], v[8:9], v[20:21] op_sel_hi:[1,0]
	s_cbranch_execz .LBB0_597

;     __device__ __forceinline__ void operator()(f32x4 (&acc)[2][2][4][2], const Unit& u, int wr, int wc, int fr, int fq) const {
;     ...
;                     const float rs = rsqrtf(rss[tok] * (1.0f / 1024.0f) + EPSV);
; #pragma unroll
;                     for (int bj = 0; bj < 2; ++bj)
; #pragma unroll
;                         for (int n = 0; n < 2; ++n) acc[ai][bj][m][n] = acc[ai][bj][m][n] * rs;
.LBB0_581:
	v_ashrrev_i32_e32 v113, 31, v112
	v_lshl_add_u64 v[8:9], v[112:113], 2, s[60:61]
	s_mov_b32 s0, 0x800000
	s_waitcnt vmcnt(0)
	v_mov_b32_e32 v8, v252
	v_fmamk_f32 v8, v8, 0x3a800000, v242
	v_mul_f32_e32 v9, 0x4b800000, v8
	v_cmp_gt_f32_e32 vcc, s0, v8
	s_nop 1
	v_cndmask_b32_e32 v8, v8, v9, vcc
	v_rsq_f32_e32 v8, v8
	s_nop 0
	v_mul_f32_e32 v9, 0x45800000, v8
	v_cndmask_b32_e32 v12, v8, v9, vcc
	v_pk_mul_f32 v[42:43], v[110:111], v[12:13] op_sel_hi:[1,0]
	v_pk_mul_f32 v[40:41], v[108:109], v[12:13] op_sel_hi:[1,0]
	v_pk_mul_f32 v[10:11], v[106:107], v[12:13] op_sel_hi:[1,0]
	v_pk_mul_f32 v[8:9], v[104:105], v[12:13] op_sel_hi:[1,0]
	v_pk_mul_f32 v[46:47], v[102:103], v[12:13] op_sel_hi:[1,0]
	v_pk_mul_f32 v[44:45], v[100:101], v[12:13] op_sel_hi:[1,0]
	v_pk_mul_f32 v[14:15], v[98:99], v[12:13] op_sel_hi:[1,0]
	v_pk_mul_f32 v[12:13], v[96:97], v[12:13] op_sel_hi:[1,0]
	s_cbranch_execz .LBB0_601

;     __device__ __forceinline__ void operator()(f32x4 (&acc)[2][2][4][2], const Unit& u, int wr, int wc, int fr, int fq) const {
;     ...
;                     const float rs = rsqrtf(rss[tok] * (1.0f / 1024.0f) + EPSV);
; #pragma unroll
;                     for (int bj = 0; bj < 2; ++bj)
; #pragma unroll
;                         for (int n = 0; n < 2; ++n) acc[ai][bj][m][n] = acc[ai][bj][m][n] * rs;
.LBB0_583:
	v_ashrrev_i32_e32 v97, 31, v96
	v_lshl_add_u64 v[98:99], v[96:97], 2, s[60:61]
	s_mov_b32 s0, 0x800000
	s_waitcnt vmcnt(0)
	v_mov_b32_e32 v97, v253
	v_fmamk_f32 v97, v97, 0x3a800000, v242
	v_mul_f32_e32 v98, 0x4b800000, v97
	v_cmp_gt_f32_e32 vcc, s0, v97
	s_nop 1
	v_cndmask_b32_e32 v97, v97, v98, vcc
	v_rsq_f32_e32 v97, v97
	s_nop 0
	v_mul_f32_e32 v98, 0x45800000, v97
	v_cndmask_b32_e32 v98, v97, v98, vcc
	v_pk_mul_f32 v[208:209], v[94:95], v[98:99] op_sel_hi:[1,0]
	v_pk_mul_f32 v[210:211], v[92:93], v[98:99] op_sel_hi:[1,0]
	v_pk_mul_f32 v[174:175], v[90:91], v[98:99] op_sel_hi:[1,0]
	v_pk_mul_f32 v[176:177], v[88:89], v[98:99] op_sel_hi:[1,0]
	v_pk_mul_f32 v[212:213], v[86:87], v[98:99] op_sel_hi:[1,0]
	v_pk_mul_f32 v[214:215], v[84:85], v[98:99] op_sel_hi:[1,0]
	v_pk_mul_f32 v[178:179], v[82:83], v[98:99] op_sel_hi:[1,0]
	v_pk_mul_f32 v[180:181], v[80:81], v[98:99] op_sel_hi:[1,0]
	s_cbranch_execz .LBB0_605

;     __device__ __forceinline__ void operator()(f32x4 (&acc)[2][2][4][2], const Unit& u, int wr, int wc, int fr, int fq) const {
;     ...
;                     const float rs = rsqrtf(rss[tok] * (1.0f / 1024.0f) + EPSV);
; #pragma unroll
;                     for (int bj = 0; bj < 2; ++bj)
; #pragma unroll
;                         for (int n = 0; n < 2; ++n) acc[ai][bj][m][n] = acc[ai][bj][m][n] * rs;
.LBB0_585:
	v_ashrrev_i32_e32 v81, 31, v80
	v_lshl_add_u64 v[82:83], v[80:81], 2, s[60:61]
	s_mov_b32 s0, 0x800000
	s_waitcnt vmcnt(0)
	v_mov_b32_e32 v81, v229
	v_fmamk_f32 v81, v81, 0x3a800000, v242
	v_mul_f32_e32 v82, 0x4b800000, v81
	v_cmp_gt_f32_e32 vcc, s0, v81
	s_nop 1
	v_cndmask_b32_e32 v81, v81, v82, vcc
	v_rsq_f32_e32 v81, v81
	s_nop 0
	v_mul_f32_e32 v82, 0x45800000, v81
	v_cndmask_b32_e32 v82, v81, v82, vcc
	v_pk_mul_f32 v[216:217], v[62:63], v[82:83] op_sel_hi:[1,0]
	v_pk_mul_f32 v[218:219], v[60:61], v[82:83] op_sel_hi:[1,0]
	v_pk_mul_f32 v[182:183], v[58:59], v[82:83] op_sel_hi:[1,0]
	v_pk_mul_f32 v[184:185], v[56:57], v[82:83] op_sel_hi:[1,0]
	v_pk_mul_f32 v[220:221], v[30:31], v[82:83] op_sel_hi:[1,0]
	v_pk_mul_f32 v[222:223], v[28:29], v[82:83] op_sel_hi:[1,0]
	v_pk_mul_f32 v[186:187], v[26:27], v[82:83] op_sel_hi:[1,0]
	v_pk_mul_f32 v[188:189], v[24:25], v[82:83] op_sel_hi:[1,0]
	s_cbranch_execz .LBB0_609

;     __device__ __forceinline__ void operator()(f32x4 (&acc)[2][2][4][2], const Unit& u, int wr, int wc, int fr, int fq) const {
;     ...
;                     const float rs = rsqrtf(rss[tok] * (1.0f / 1024.0f) + EPSV);
; #pragma unroll
;                     for (int bj = 0; bj < 2; ++bj)
; #pragma unroll
;                         for (int n = 0; n < 2; ++n) acc[ai][bj][m][n] = acc[ai][bj][m][n] * rs;
.LBB0_587:
	v_ashrrev_i32_e32 v81, 31, v80
	v_lshl_add_u64 v[24:25], v[80:81], 2, s[60:61]
	s_mov_b32 s0, 0x800000
	s_waitcnt vmcnt(0)
	v_mov_b32_e32 v24, v230
	v_fmamk_f32 v24, v24, 0x3a800000, v242
	v_mul_f32_e32 v25, 0x4b800000, v24
	v_cmp_gt_f32_e32 vcc, s0, v24
	s_nop 1
	v_cndmask_b32_e32 v24, v24, v25, vcc
	v_rsq_f32_e32 v24, v24
	s_nop 0
	v_mul_f32_e32 v25, 0x45800000, v24
	v_cndmask_b32_e32 v28, v24, v25, vcc
	v_pk_mul_f32 v[58:59], v[78:79], v[28:29] op_sel_hi:[1,0]
	v_pk_mul_f32 v[56:57], v[76:77], v[28:29] op_sel_hi:[1,0]
	v_pk_mul_f32 v[26:27], v[74:75], v[28:29] op_sel_hi:[1,0]
	v_pk_mul_f32 v[24:25], v[72:73], v[28:29] op_sel_hi:[1,0]
	v_pk_mul_f32 v[62:63], v[70:71], v[28:29] op_sel_hi:[1,0]
	v_pk_mul_f32 v[60:61], v[68:69], v[28:29] op_sel_hi:[1,0]
	v_pk_mul_f32 v[30:31], v[66:67], v[28:29] op_sel_hi:[1,0]
	v_pk_mul_f32 v[28:29], v[64:65], v[28:29] op_sel_hi:[1,0]
	s_cbranch_execnz .LBB0_616
	s_branch .LBB0_613

; #define LAS __attribute__((address_space(3)))
;     template <bool BND> __device__ __forceinline__ void conv_gate(f32x4 (&acc)[2][2][4][2], const Unit& u, int wr, int wc, int fr, int fq, int tok0, int pcol) const {
;         const int fcol = u.pn * 128 + pcol;
; #pragma unroll
;         for (int n = 0; n < 2; ++n) {
;             f32x4 w0[2], w1[2], w2[2], bb[2];
; #pragma unroll
;             for (int bj = 0; bj < 2; ++bj) { const int c = bj * DFF + fcol + 4 * n;
;                 w0[bj] = *(const f32x4*)(convw + c); w1[bj] = *(const f32x4*)(convw + 2 * DFF + c); w2[bj] = *(const f32x4*)(convw + 4 * DFF + c); bb[bj] = *(const f32x4*)(convb + c); }
; #pragma unroll
;             for (int ai = 0; ai < 2; ++ai) {
;                 const int blk = 2 * ai + wr;
;                 f32x4 pe[2], ne[2];
; #pragma unroll
;                 for (int bj = 0; bj < 2; ++bj) {
;                     pe[bj] = blk > 0 ? *(const LAS f32x4*)(edge + ((blk - 1) * 2 + 1) * 256 + 128 * bj + pcol + 4 * n) : (f32x4){0.f, 0.f, 0.f, 0.f};
;                     ne[bj] = blk < 3 ? *(const LAS f32x4*)(edge + ((blk + 1) * 2 + 0) * 256 + 128 * bj + pcol + 4 * n) : (f32x4){0.f, 0.f, 0.f, 0.f};
;     __device__ __forceinline__ void operator()(f32x4 (&acc)[2][2][4][2], const Unit& u, int wr, int wc, int fr, int fq) const {
;     ...
;         asm volatile("s_waitcnt lgkmcnt(0)\n\ts_barrier" ::: "memory");
.LBB0_629:
	s_or_b64 exec, exec, s[0:1]
	v_lshl_add_u32 v190, s10, 7, v80
	v_readlane_b32 s4, v255, 0
	v_readlane_b32 s8, v255, 4
	v_readlane_b32 s9, v255, 5
	v_add_u32_e32 v80, 0xb00, v190
	v_ashrrev_i32_e32 v191, 31, v190
	v_readlane_b32 s0, v255, 31
	v_readlane_b32 s8, v255, 33
	v_ashrrev_i32_e32 v81, 31, v80
	v_lshlrev_b64 v[64:65], 2, v[190:191]
	v_readlane_b32 s5, v255, 1
	v_readlane_b32 s6, v255, 2
	v_readlane_b32 s7, v255, 3
	v_readlane_b32 s1, v255, 32
	v_readlane_b32 s9, v255, 34
	v_lshlrev_b64 v[80:81], 2, v[80:81]
	s_waitcnt lgkmcnt(0)
	v_lshl_add_u64 v[224:225], s[4:5], 0, v[64:65]
	v_lshl_add_u64 v[66:67], s[0:1], 0, v[64:65]
	v_lshl_add_u64 v[68:69], s[8:9], 0, v[64:65]
	v_lshl_add_u64 v[226:227], s[6:7], 0, v[64:65]
	v_lshl_add_u64 v[82:83], s[4:5], 0, v[80:81]
	global_load_dwordx4 v[72:75], v[224:225], off
	global_load_dwordx4 v[76:79], v[66:67], off
	s_nop 0
	global_load_dwordx4 v[68:71], v[68:69], off
	v_lshl_add_u64 v[84:85], s[0:1], 0, v[80:81]
	global_load_dwordx4 v[64:67], v[226:227], off
	global_load_dwordx4 v[92:95], v[82:83], off
	global_load_dwordx4 v[88:91], v[84:85], off
	v_lshl_add_u64 v[82:83], s[8:9], 0, v[80:81]
	v_lshl_add_u64 v[80:81], s[6:7], 0, v[80:81]
	global_load_dwordx4 v[84:87], v[82:83], off
	v_readlane_b32 s4, v255, 25
	global_load_dwordx4 v[80:83], v[80:81], off
	s_waitcnt lgkmcnt(0)
	s_barrier
	v_readlane_b32 s0, v255, 35
	v_readlane_b32 s5, v255, 26
	v_readlane_b32 s10, v255, 6
	v_readlane_b32 s11, v255, 7
	v_add_u32_e32 v247, s0, v96
	v_cndmask_b32_e64 v96, 0, 1, s[4:5]
	v_cmp_eq_u32_e64 s[8:9], 15, v228
	v_cmp_eq_u32_e64 s[6:7], 0, v228
	s_mov_b64 s[0:1], -1
	s_and_b64 vcc, exec, s[12:13]
	v_cmp_ne_u32_e64 s[10:11], 1, v96
	s_cbranch_vccz .LBB0_695
	s_and_b64 s[14:15], s[6:7], s[80:81]
	s_andn2_b64 s[16:17], s[8:9], s[80:81]
	s_mov_b32 s20, 0x16000
	s_mov_b32 s21, 0
	s_mov_b32 s22, 0x6e000
	s_mov_b32 s23, 0
	s_mov_b32 s24, 0xfff0e000
	s_mov_b32 s25, -1
	v_mov_b64_e32 v[140:141], s[88:89]
	s_movk_i32 s4, 0x1600
	v_mad_i64_i32 v[140:141], s[12:13], v152, s4, v[140:141]
	v_lshl_add_u64 v[140:141], v[190:191], 1, v[140:141]
	ds_read_b128 v[132:135], v247
	ds_read_b128 v[136:139], v247 offset:512
	s_waitcnt vmcnt(0)
	s_waitcnt lgkmcnt(0)
	s_cmp_eq_u64 s[80:81], 0
	s_cbranch_scc1 .Lconv_keep_1
	v_mov_b32_e32 v132, 0
	v_mov_b32_e32 v133, 0
	v_mov_b32_e32 v134, 0
	v_mov_b32_e32 v135, 0
	v_mov_b32_e32 v136, 0
	v_mov_b32_e32 v137, 0
	v_mov_b32_e32 v138, 0
	v_mov_b32_e32 v139, 0
